# v057 + conv (P2) loop: preheader-only waits removed, counted waits before register rotation so prefetch loads and store drain overlap compute; P0: loop-invariant gate-bias loads hoisted (no per-row vm
# speedup vs baseline: 1.0087x; 1.0087x over previous
; DI int opq(int x) { asm volatile("" : "+v"(x)); return x; }
; template <bool GATES>
; DI void rmsnorm_rows(const float* X, const float* g, bf16_t* U, const float* Wg, const float* b_i, const float* b_f, float* LI, float* LF) {
;     const int tid_ = opq(threadIdx.x), lane = tid_ & 63, wid = tid_ >> 6;
;     const int gw = blockIdx.x * 8 + wid, nw = gridDim.x * 8;
;     f32x4 g4[4];
; #pragma unroll
;     for (int i = 0; i < 4; ++i) g4[i] = ((const f32x4*)g)[lane + 64 * i];
;     f32x4 nx[4];
; #pragma unroll
;     for (int i = 0; i < 4; ++i) nx[i] = ((const f32x4*)(X + (size_t)gw * 1024))[lane + 64 * i];
;     ...
;                 const int b = row >> 11, s = row & 2047, hh = lane & 3;
;                 if (lane < 4) LI[(size_t)(b * 4 + hh) * S_ + s] = val + b_i[hh];
;                 else { const float xx = val + b_f[hh]; LF[(size_t)(b * 4 + hh) * S_ + s] = fminf(xx, 0.f) - log1pf(__expf(-fabsf(xx))); }
.LBB0_100:
	s_or_b64 exec, exec, s[0:1]
	v_mov_b32_e32 v32, v192
	s_waitcnt lgkmcnt(0)
	s_barrier
	v_readlane_b32 s0, v244, 21
	v_ashrrev_i32_e32 v0, 6, v32
	s_mov_b32 s75, s49
	v_add_u32_e32 v164, s0, v0
	s_mov_b32 s0, 0x10000
	v_cmp_gt_i32_e32 vcc, s0, v164
	s_and_saveexec_b64 s[78:79], vcc
	s_cbranch_execz .LBB0_109
	v_ashrrev_i32_e32 v165, 31, v164
	v_readlane_b32 s36, v246, 53
	v_and_b32_e32 v163, 63, v32
	v_lshlrev_b64 v[0:1], 12, v[164:165]
	v_readlane_b32 s37, v246, 54
	v_lshlrev_b32_e32 v160, 4, v163
	v_readlane_b32 s38, v246, 55
	v_lshl_add_u64 v[0:1], s[36:37], 0, v[0:1]
	v_lshl_add_u64 v[0:1], v[0:1], 0, v[160:161]
	v_readlane_b32 s39, v246, 56
	global_load_dwordx4 v[8:11], v[0:1], off offset:3072
	global_load_dwordx4 v[16:19], v[0:1], off offset:2048
	global_load_dwordx4 v[24:27], v[0:1], off offset:1024
	global_load_dwordx4 v[28:31], v[0:1], off
	s_nop 0
	global_load_dwordx4 v[0:3], v160, s[38:39]
	global_load_dwordx4 v[4:7], v160, s[38:39] offset:1024
	global_load_dwordx4 v[12:15], v160, s[38:39] offset:2048
	global_load_dwordx4 v[20:23], v160, s[38:39] offset:3072
	v_and_b32_e32 v198, 3, v32
	v_add_u32_e32 v156, 0, v160
	v_lshlrev_b32_e32 v32, 2, v198
	v_mov_b32_e32 v33, v161
	v_lshl_add_u64 v[166:167], s[8:9], 0, v[32:33]
	v_lshl_add_u64 v[168:169], s[6:7], 0, v[32:33]
	global_load_dword v242, v[166:167], off
	global_load_dword v243, v[168:169], off
	s_waitcnt vmcnt(0)
	ds_read_b128 v[32:35], v156 offset:20480
	ds_read_b128 v[36:39], v156 offset:21504
	ds_read_b128 v[40:43], v156 offset:22528
	ds_read_b128 v[44:47], v156 offset:23552
	ds_read_b128 v[48:51], v156 offset:24576
	ds_read_b128 v[52:55], v156 offset:25600
	ds_read_b128 v[56:59], v156 offset:26624
	ds_read_b128 v[60:63], v156 offset:27648
	ds_read_b128 v[64:67], v156 offset:28672
	ds_read_b128 v[68:71], v156 offset:29696
	ds_read_b128 v[72:75], v156 offset:30720
	ds_read_b128 v[76:79], v156 offset:31744
	ds_read_b128 v[80:83], v156 offset:32768
	ds_read_b128 v[84:87], v156 offset:33792
	ds_read_b128 v[88:91], v156 offset:34816
	ds_read_b128 v[92:95], v156 offset:35840
	ds_read_b128 v[96:99], v156 offset:36864
	ds_read_b128 v[100:103], v156 offset:37888
	ds_read_b128 v[104:107], v156 offset:38912
	ds_read_b128 v[108:111], v156 offset:39936
	ds_read_b128 v[112:115], v156 offset:40960
	ds_read_b128 v[116:119], v156 offset:41984
	ds_read_b128 v[120:123], v156 offset:43008
	ds_read_b128 v[124:127], v156 offset:44032
	ds_read_b128 v[128:131], v156 offset:45056
	ds_read_b128 v[132:135], v156 offset:46080
	ds_read_b128 v[136:139], v156 offset:47104
	ds_read_b128 v[140:143], v156 offset:48128
	ds_read_b128 v[144:147], v156 offset:49152
	ds_read_b128 v[148:151], v156 offset:50176
	ds_read_b128 v[152:155], v156 offset:51200
	ds_read_b128 v[156:159], v156 offset:52224
	v_cmp_eq_u32_e64 s[0:1], 4, v163
	v_readlane_b32 s47, v245, 0
	v_readlane_b32 s48, v245, 1
	v_readlane_b32 s49, v245, 2
	v_readlane_b32 s50, v245, 3
	v_readlane_b32 s51, v245, 4
	v_writelane_b32 v245, s0, 21
	v_lshlrev_b64 v[170:171], 11, v[164:165]
	v_readlane_b32 s40, v246, 57
	v_writelane_b32 v245, s1, 22
	v_cmp_eq_u32_e64 s[0:1], 5, v163
	v_readlane_b32 s41, v246, 58
	v_readlane_b32 s42, v246, 59
	v_writelane_b32 v245, s0, 23
	v_readlane_b32 s43, v246, 60
	v_readlane_b32 s44, v246, 61
	v_writelane_b32 v245, s1, 24
	v_cmp_eq_u32_e64 s[0:1], 6, v163
	v_readlane_b32 s45, v246, 62
	v_lshl_or_b32 v170, v163, 3, v170
	v_writelane_b32 v245, s0, 25
	v_cmp_gt_u32_e32 vcc, 8, v163
	v_cmp_lt_u32_e64 s[38:39], 3, v163
	v_writelane_b32 v245, s1, 26
	v_cmp_eq_u32_e64 s[0:1], 7, v163
	v_cmp_eq_u32_e64 s[40:41], 1, v163
	v_cmp_eq_u32_e64 s[42:43], 2, v163
	v_cmp_eq_u32_e64 s[44:45], 3, v163
	v_writelane_b32 v245, s0, 27
	v_lshl_add_u64 v[170:171], s[20:21], 0, v[170:171]
	s_mov_b64 s[2:3], 0
	v_lshl_add_u64 v[172:173], s[36:37], 0, v[160:161]
	v_readlane_b32 s46, v246, 63
	v_writelane_b32 v245, s1, 28
	s_branch .LBB0_104

; DI unsigned pk2(float a, float b) { f32x2 v = {a, b}; bf2_t r = __builtin_convertvector(v, bf2_t); return __builtin_bit_cast(unsigned, r); }
; template <bool GATES>
; DI void rmsnorm_rows(const float* X, const float* g, bf16_t* U, const float* Wg, const float* b_i, const float* b_f, float* LI, float* LF) {
;     ...
;     for (int row = gw; row < T_; row += nw) {
;         f32x4 v[4]; float ss = 0.f;
;         const int rown = (row + nw < T_) ? row + nw : row;
; #pragma unroll
;         for (int i = 0; i < 4; ++i) { v[i] = nx[i]; nx[i] = ((const f32x4*)(X + (size_t)rown * 1024))[lane + 64 * i]; ss += v[i][0] * v[i][0] + v[i][1] * v[i][1] + v[i][2] * v[i][2] + v[i][3] * v[i][3]; }
;         ss = wave_sum(ss);
;         const float rs = __builtin_amdgcn_rsqf(ss * (1.f / 1024.f) + EPS_);
; #pragma unroll
;         for (int i = 0; i < 4; ++i) { v[i] = v[i] * rs * g4[i]; u32x2 w; w[0] = pk2(v[i][0], v[i][1]); w[1] = pk2(v[i][2], v[i][3]); ((u32x2*)(U + (size_t)row * 1024))[lane + 64 * i] = w; }
;         if (GATES) {
;             float d[8];
; #pragma unroll
;             for (int j = 0; j < 8; ++j) { float s = 0.f;
; #pragma unroll
;                 for (int i = 0; i < 4; ++i) { const f32x4 w = ((const f32x4*)(Wg + j * 1024))[lane + 64 * i]; s += v[i][0] * w[0] + v[i][1] * w[1] + v[i][2] * w[2] + v[i][3] * w[3]; }
;                 d[j] = wave_sum(s); }
.LBB0_104:
	s_waitcnt vmcnt(4)
	v_mov_b64_e32 v[176:177], v[30:31]
	v_mov_b64_e32 v[182:183], v[26:27]
	v_mov_b64_e32 v[174:175], v[28:29]
	v_mov_b64_e32 v[180:181], v[24:25]
	v_mov_b64_e32 v[186:187], v[18:19]
	v_mov_b64_e32 v[184:185], v[16:17]
	v_mov_b64_e32 v[202:203], v[10:11]
	v_mov_b32_e32 v16, v181
	v_mov_b32_e32 v17, v175
	v_mov_b64_e32 v[200:201], v[8:9]
	v_mov_b32_e32 v10, v180
	v_mov_b32_e32 v11, v174
	v_pk_mul_f32 v[16:17], v[16:17], v[16:17]
	v_mov_b32_e32 v18, v201
	v_pk_fma_f32 v[10:11], v[10:11], v[10:11], v[16:17]
	v_mov_b32_e32 v16, v182
	v_mov_b32_e32 v17, v176
	v_pk_fma_f32 v[10:11], v[16:17], v[16:17], v[10:11]
	v_mov_b32_e32 v16, v183
	v_mov_b32_e32 v17, v177
	v_mov_b32_e32 v19, v185
	v_pk_fma_f32 v[10:11], v[16:17], v[16:17], v[10:11]
	v_mov_b32_e32 v16, v200
	v_mov_b32_e32 v17, v184
	v_pk_mul_f32 v[18:19], v[18:19], v[18:19]
	v_add_f32_e32 v10, v10, v11
	v_pk_fma_f32 v[16:17], v[16:17], v[16:17], v[18:19]
	v_mov_b32_e32 v18, v202
	v_mov_b32_e32 v19, v186
	v_pk_fma_f32 v[16:17], v[18:19], v[18:19], v[16:17]
	v_mov_b32_e32 v18, v203
	v_mov_b32_e32 v19, v187
	v_pk_fma_f32 v[16:17], v[18:19], v[18:19], v[16:17]
	v_readlane_b32 s0, v246, 47
	v_add_f32_e32 v10, v17, v10
	v_add_f32_e32 v10, v16, v10
	v_add_u32_e32 v165, s0, v164
	s_mov_b32 s0, 0xffff
	v_add_f32_dpp v10, v10, v10 quad_perm:[1,0,3,2] row_mask:0xf bank_mask:0xf bound_ctrl:1
	v_readlane_b32 s1, v246, 48
	v_cmp_lt_i32_e64 s[54:55], s0, v165
	v_add_f32_dpp v10, v10, v10 quad_perm:[2,3,0,1] row_mask:0xf bank_mask:0xf bound_ctrl:1
	s_mov_b32 s0, 0x10000
	v_cmp_gt_i32_e64 s[0:1], s0, v165
	v_add_f32_dpp v10, v10, v10 row_half_mirror row_mask:0xf bank_mask:0xf bound_ctrl:1
	s_nop 0
	v_cndmask_b32_e64 v8, v164, v165, s[0:1]
	v_add_f32_dpp v10, v10, v10 row_mirror row_mask:0xf bank_mask:0xf bound_ctrl:1
	v_ashrrev_i32_e32 v9, 31, v8
	v_readlane_b32 s22, v10, 16
	v_readlane_b32 s23, v10, 48
	v_readlane_b32 s0, v10, 0
	v_readlane_b32 s1, v10, 32
	v_mov_b32_e32 v10, s22
	v_mov_b32_e32 v11, s23
	v_pk_add_f32 v[10:11], s[0:1], v[10:11]
	v_lshlrev_b64 v[8:9], 12, v[8:9]
	v_add_f32_e32 v10, v10, v11
	v_fmamk_f32 v10, v10, 0x3a800000, v191
	v_rsq_f32_e32 v160, v10
	v_lshl_add_u64 v[8:9], v[172:173], 0, v[8:9]
	global_load_dwordx4 v[28:31], v[8:9], off
	global_load_dwordx4 v[24:27], v[8:9], off offset:1024
	global_load_dwordx4 v[16:19], v[8:9], off offset:2048
	s_nop 0
	global_load_dwordx4 v[8:11], v[8:9], off offset:3072
	v_pk_mul_f32 v[178:179], v[174:175], v[160:161] op_sel_hi:[1,0]
	v_pk_mul_f32 v[174:175], v[176:177], v[160:161] op_sel_hi:[1,0]
	s_waitcnt vmcnt(7)
	v_pk_mul_f32 v[178:179], v[0:1], v[178:179]
	v_pk_mul_f32 v[174:175], v[2:3], v[174:175]
	v_cvt_pk_bf16_f32 v176, v178, v179
	v_cvt_pk_bf16_f32 v177, v174, v175
	global_store_dwordx2 v[170:171], v[176:177], off
	v_pk_mul_f32 v[180:181], v[180:181], v[160:161] op_sel_hi:[1,0]
	v_pk_mul_f32 v[176:177], v[182:183], v[160:161] op_sel_hi:[1,0]
	s_waitcnt vmcnt(7)
	v_pk_mul_f32 v[182:183], v[4:5], v[180:181]
	v_pk_mul_f32 v[176:177], v[6:7], v[176:177]
	v_cvt_pk_bf16_f32 v180, v182, v183
	v_cvt_pk_bf16_f32 v181, v176, v177
	global_store_dwordx2 v[170:171], v[180:181], off offset:512
	v_pk_mul_f32 v[184:185], v[184:185], v[160:161] op_sel_hi:[1,0]
	v_pk_mul_f32 v[180:181], v[186:187], v[160:161] op_sel_hi:[1,0]
	s_waitcnt vmcnt(7)
	v_pk_mul_f32 v[186:187], v[12:13], v[184:185]
	v_pk_mul_f32 v[180:181], v[14:15], v[180:181]
	v_cvt_pk_bf16_f32 v184, v186, v187
	v_cvt_pk_bf16_f32 v185, v180, v181
	global_store_dwordx2 v[170:171], v[184:185], off offset:1024
	v_pk_mul_f32 v[188:189], v[200:201], v[160:161] op_sel_hi:[1,0]
	v_pk_mul_f32 v[184:185], v[202:203], v[160:161] op_sel_hi:[1,0]
	s_waitcnt lgkmcnt(14)
	v_mul_f32_e32 v160, v33, v179
	v_fmac_f32_e32 v160, v32, v178
	v_mul_f32_e32 v163, v37, v183
	v_fmac_f32_e32 v160, v34, v174
	v_fmac_f32_e32 v163, v36, v182
	v_fmac_f32_e32 v160, v35, v175
	v_fmac_f32_e32 v163, v38, v176
	v_add_f32_e32 v160, 0, v160
	v_fmac_f32_e32 v163, v39, v177
	v_add_f32_e32 v160, v163, v160
	v_mul_f32_e32 v163, v41, v187
	v_fmac_f32_e32 v163, v40, v186
	v_fmac_f32_e32 v163, v42, v180
	s_waitcnt vmcnt(7)
	v_pk_mul_f32 v[188:189], v[20:21], v[188:189]
	v_fmac_f32_e32 v163, v43, v181
	v_add_f32_e32 v160, v163, v160
	v_mul_f32_e32 v163, v45, v189
	v_pk_mul_f32 v[184:185], v[22:23], v[184:185]
	v_fmac_f32_e32 v163, v44, v188
	v_fmac_f32_e32 v163, v46, v184
	v_fmac_f32_e32 v163, v47, v185
	v_add_f32_e32 v160, v163, v160
	v_mul_f32_e32 v163, v183, v53
	v_fmac_f32_e32 v163, v182, v52
	v_add_f32_dpp v160, v160, v160 quad_perm:[1,0,3,2] row_mask:0xf bank_mask:0xf bound_ctrl:1
	v_fmac_f32_e32 v163, v176, v54
	v_fmac_f32_e32 v163, v177, v55
	v_add_f32_dpp v160, v160, v160 quad_perm:[2,3,0,1] row_mask:0xf bank_mask:0xf bound_ctrl:1
	v_cvt_pk_bf16_f32 v200, v188, v189
	v_cvt_pk_bf16_f32 v201, v184, v185
	v_add_f32_dpp v160, v160, v160 row_half_mirror row_mask:0xf bank_mask:0xf bound_ctrl:1
	global_store_dwordx2 v[170:171], v[200:201], off offset:1536
	s_nop 0
	v_add_f32_dpp v160, v160, v160 row_mirror row_mask:0xf bank_mask:0xf bound_ctrl:1
	s_nop 0
	v_readlane_b32 s0, v160, 0
	v_readlane_b32 s58, v160, 16
	v_readlane_b32 s1, v160, 32
	v_readlane_b32 s59, v160, 48
	v_mul_f32_e32 v160, v179, v49
	v_fmac_f32_e32 v160, v178, v48
	v_fmac_f32_e32 v160, v174, v50
	v_fmac_f32_e32 v160, v175, v51
	v_add_f32_e32 v160, 0, v160
	v_add_f32_e32 v160, v160, v163
	v_mul_f32_e32 v163, v187, v57
	v_fmac_f32_e32 v163, v186, v56
	v_fmac_f32_e32 v163, v180, v58
	v_fmac_f32_e32 v163, v181, v59
	v_add_f32_e32 v160, v160, v163
	v_mul_f32_e32 v163, v189, v61
	v_fmac_f32_e32 v163, v188, v60
	v_fmac_f32_e32 v163, v184, v62
; template <bool GATES>
; DI void rmsnorm_rows(const float* X, const float* g, bf16_t* U, const float* Wg, const float* b_i, const float* b_f, float* LI, float* LF) {
;     ...
;             for (int j = 0; j < 8; ++j) { float s = 0.f;
; #pragma unroll
;                 for (int i = 0; i < 4; ++i) { const f32x4 w = ((const f32x4*)(Wg + j * 1024))[lane + 64 * i]; s += v[i][0] * w[0] + v[i][1] * w[1] + v[i][2] * w[2] + v[i][3] * w[3]; }
;                 d[j] = wave_sum(s); }
	v_fmac_f32_e32 v163, v185, v63
	v_add_f32_e32 v160, v160, v163
	v_mul_f32_e32 v163, v183, v69
	v_fmac_f32_e32 v163, v182, v68
	v_add_f32_dpp v160, v160, v160 quad_perm:[1,0,3,2] row_mask:0xf bank_mask:0xf bound_ctrl:1
	v_fmac_f32_e32 v163, v176, v70
	v_fmac_f32_e32 v163, v177, v71
	v_add_f32_dpp v160, v160, v160 quad_perm:[2,3,0,1] row_mask:0xf bank_mask:0xf bound_ctrl:1
	s_nop 1
	v_add_f32_dpp v160, v160, v160 row_half_mirror row_mask:0xf bank_mask:0xf bound_ctrl:1
	s_nop 1
	v_add_f32_dpp v160, v160, v160 row_mirror row_mask:0xf bank_mask:0xf bound_ctrl:1
	s_nop 0
	v_readlane_b32 s96, v160, 0
	v_readlane_b32 s61, v160, 16
	v_readlane_b32 s60, v160, 32
	v_readlane_b32 s27, v160, 48
	v_mul_f32_e32 v160, v179, v65
	v_fmac_f32_e32 v160, v178, v64
	v_fmac_f32_e32 v160, v174, v66
	v_fmac_f32_e32 v160, v175, v67
	v_add_f32_e32 v160, 0, v160
	v_add_f32_e32 v160, v160, v163
	v_mul_f32_e32 v163, v187, v73
	v_fmac_f32_e32 v163, v186, v72
	v_fmac_f32_e32 v163, v180, v74
	v_fmac_f32_e32 v163, v181, v75
	v_add_f32_e32 v160, v160, v163
	v_mul_f32_e32 v163, v189, v77
	v_fmac_f32_e32 v163, v188, v76
	v_fmac_f32_e32 v163, v184, v78
	v_fmac_f32_e32 v163, v185, v79
	v_add_f32_e32 v160, v160, v163
	v_mul_f32_e32 v163, v183, v85
	v_fmac_f32_e32 v163, v182, v84
	v_add_f32_dpp v160, v160, v160 quad_perm:[1,0,3,2] row_mask:0xf bank_mask:0xf bound_ctrl:1
	v_fmac_f32_e32 v163, v176, v86
	v_fmac_f32_e32 v163, v177, v87
	v_add_f32_dpp v160, v160, v160 quad_perm:[2,3,0,1] row_mask:0xf bank_mask:0xf bound_ctrl:1
	s_nop 1
	v_add_f32_dpp v160, v160, v160 row_half_mirror row_mask:0xf bank_mask:0xf bound_ctrl:1
	s_nop 1
	v_add_f32_dpp v160, v160, v160 row_mirror row_mask:0xf bank_mask:0xf bound_ctrl:1
	s_nop 0
	v_readlane_b32 s33, v160, 0
	v_readlane_b32 s35, v160, 16
	v_readlane_b32 s34, v160, 32
	v_readlane_b32 s46, v160, 48
	v_mul_f32_e32 v160, v179, v81
	v_fmac_f32_e32 v160, v178, v80
	v_fmac_f32_e32 v160, v174, v82
	v_fmac_f32_e32 v160, v175, v83
	v_add_f32_e32 v160, 0, v160
	v_add_f32_e32 v160, v160, v163
	v_mul_f32_e32 v163, v187, v89
	v_fmac_f32_e32 v163, v186, v88
	v_fmac_f32_e32 v163, v180, v90
	v_fmac_f32_e32 v163, v181, v91
	v_add_f32_e32 v160, v160, v163
	v_mul_f32_e32 v163, v189, v93
	v_fmac_f32_e32 v163, v188, v92
	v_fmac_f32_e32 v163, v184, v94
	v_fmac_f32_e32 v163, v185, v95
	v_add_f32_e32 v160, v160, v163
	v_mul_f32_e32 v163, v183, v101
	v_fmac_f32_e32 v163, v182, v100
	v_add_f32_dpp v160, v160, v160 quad_perm:[1,0,3,2] row_mask:0xf bank_mask:0xf bound_ctrl:1
	v_fmac_f32_e32 v163, v176, v102
	v_fmac_f32_e32 v163, v177, v103
	v_add_f32_dpp v160, v160, v160 quad_perm:[2,3,0,1] row_mask:0xf bank_mask:0xf bound_ctrl:1
	s_nop 1
	v_add_f32_dpp v160, v160, v160 row_half_mirror row_mask:0xf bank_mask:0xf bound_ctrl:1
	s_nop 1
	v_add_f32_dpp v160, v160, v160 row_mirror row_mask:0xf bank_mask:0xf bound_ctrl:1
	s_nop 0
	v_readlane_b32 s47, v160, 0
	v_readlane_b32 s49, v160, 16
	v_readlane_b32 s48, v160, 32
	v_readlane_b32 s50, v160, 48
	v_mul_f32_e32 v160, v179, v97
	v_fmac_f32_e32 v160, v178, v96
	v_fmac_f32_e32 v160, v174, v98
	v_fmac_f32_e32 v160, v175, v99
	v_add_f32_e32 v160, 0, v160
	v_add_f32_e32 v160, v160, v163
	s_waitcnt lgkmcnt(13)
	v_mul_f32_e32 v163, v187, v105
	v_fmac_f32_e32 v163, v186, v104
	v_fmac_f32_e32 v163, v180, v106
	v_fmac_f32_e32 v163, v181, v107
	v_add_f32_e32 v160, v160, v163
	s_waitcnt lgkmcnt(12)
	v_mul_f32_e32 v163, v189, v109
	v_fmac_f32_e32 v163, v188, v108
	v_fmac_f32_e32 v163, v184, v110
	v_fmac_f32_e32 v163, v185, v111
	v_add_f32_e32 v160, v160, v163
	s_waitcnt lgkmcnt(10)
	v_mul_f32_e32 v163, v183, v117
	v_fmac_f32_e32 v163, v182, v116
	v_add_f32_dpp v160, v160, v160 quad_perm:[1,0,3,2] row_mask:0xf bank_mask:0xf bound_ctrl:1
	v_fmac_f32_e32 v163, v176, v118
	v_fmac_f32_e32 v163, v177, v119
	v_add_f32_dpp v160, v160, v160 quad_perm:[2,3,0,1] row_mask:0xf bank_mask:0xf bound_ctrl:1
	s_nop 1
	v_add_f32_dpp v160, v160, v160 row_half_mirror row_mask:0xf bank_mask:0xf bound_ctrl:1
	s_nop 1
	v_add_f32_dpp v160, v160, v160 row_mirror row_mask:0xf bank_mask:0xf bound_ctrl:1
	s_nop 0
	v_readlane_b32 s51, v160, 0
	v_readlane_b32 s53, v160, 16
	v_readlane_b32 s52, v160, 32
	v_readlane_b32 s36, v160, 48
	v_mul_f32_e32 v160, v179, v113
	v_fmac_f32_e32 v160, v178, v112
	v_fmac_f32_e32 v160, v174, v114
	v_fmac_f32_e32 v160, v175, v115
	v_add_f32_e32 v160, 0, v160
	v_add_f32_e32 v160, v160, v163
	s_waitcnt lgkmcnt(9)
	v_mul_f32_e32 v163, v187, v121
	v_fmac_f32_e32 v163, v186, v120
	v_fmac_f32_e32 v163, v180, v122
	v_fmac_f32_e32 v163, v181, v123
	v_add_f32_e32 v160, v160, v163
	s_waitcnt lgkmcnt(8)
	v_mul_f32_e32 v163, v189, v125
	v_fmac_f32_e32 v163, v188, v124
	v_fmac_f32_e32 v163, v184, v126
	v_fmac_f32_e32 v163, v185, v127
	v_add_f32_e32 v160, v160, v163
	s_waitcnt lgkmcnt(6)
	v_mul_f32_e32 v163, v183, v133
	v_fmac_f32_e32 v163, v182, v132
	v_add_f32_dpp v160, v160, v160 quad_perm:[1,0,3,2] row_mask:0xf bank_mask:0xf bound_ctrl:1
	v_fmac_f32_e32 v163, v176, v134
	v_fmac_f32_e32 v163, v177, v135
	v_add_f32_dpp v160, v160, v160 quad_perm:[2,3,0,1] row_mask:0xf bank_mask:0xf bound_ctrl:1
	s_nop 1
	v_add_f32_dpp v160, v160, v160 row_half_mirror row_mask:0xf bank_mask:0xf bound_ctrl:1
	s_nop 1
	v_add_f32_dpp v160, v160, v160 row_mirror row_mask:0xf bank_mask:0xf bound_ctrl:1
	s_nop 0
	v_readlane_b32 s37, v160, 0
	v_readlane_b32 s65, v160, 16
	v_readlane_b32 s64, v160, 32
	v_readlane_b32 s66, v160, 48
	v_mul_f32_e32 v160, v179, v129
	v_fmac_f32_e32 v160, v178, v128
	v_fmac_f32_e32 v160, v174, v130
	v_fmac_f32_e32 v160, v175, v131
	v_add_f32_e32 v160, 0, v160
	v_add_f32_e32 v160, v160, v163
	s_waitcnt lgkmcnt(5)
; template <bool GATES>
; DI void rmsnorm_rows(const float* X, const float* g, bf16_t* U, const float* Wg, const float* b_i, const float* b_f, float* LI, float* LF) {
;     ...
;             for (int j = 0; j < 8; ++j) { float s = 0.f;
; #pragma unroll
;                 for (int i = 0; i < 4; ++i) { const f32x4 w = ((const f32x4*)(Wg + j * 1024))[lane + 64 * i]; s += v[i][0] * w[0] + v[i][1] * w[1] + v[i][2] * w[2] + v[i][3] * w[3]; }
;                 d[j] = wave_sum(s); }
;             float val = d[0];
; #pragma unroll
;             for (int j = 1; j < 8; ++j) val = (lane == j) ? d[j] : val;
;             if (lane < 8) {
	v_mul_f32_e32 v163, v187, v137
	v_fmac_f32_e32 v163, v186, v136
	v_fmac_f32_e32 v163, v180, v138
	v_fmac_f32_e32 v163, v181, v139
	v_add_f32_e32 v160, v160, v163
	s_waitcnt lgkmcnt(4)
	v_mul_f32_e32 v163, v189, v141
	v_fmac_f32_e32 v163, v188, v140
	v_fmac_f32_e32 v163, v184, v142
	v_fmac_f32_e32 v163, v185, v143
	v_add_f32_e32 v160, v160, v163
	s_waitcnt lgkmcnt(2)
	v_mul_f32_e32 v163, v183, v149
	v_fmac_f32_e32 v163, v182, v148
	v_add_f32_dpp v160, v160, v160 quad_perm:[1,0,3,2] row_mask:0xf bank_mask:0xf bound_ctrl:1
	v_fmac_f32_e32 v163, v176, v150
	v_fmac_f32_e32 v163, v177, v151
	v_add_f32_dpp v160, v160, v160 quad_perm:[2,3,0,1] row_mask:0xf bank_mask:0xf bound_ctrl:1
	s_nop 1
	v_add_f32_dpp v160, v160, v160 row_half_mirror row_mask:0xf bank_mask:0xf bound_ctrl:1
	s_nop 1
	v_add_f32_dpp v160, v160, v160 row_mirror row_mask:0xf bank_mask:0xf bound_ctrl:1
	s_nop 0
	v_readlane_b32 s67, v160, 0
	v_readlane_b32 s69, v160, 16
	v_readlane_b32 s68, v160, 32
	v_readlane_b32 s70, v160, 48
	v_mul_f32_e32 v160, v179, v145
	v_fmac_f32_e32 v160, v178, v144
	v_fmac_f32_e32 v160, v174, v146
	v_fmac_f32_e32 v160, v175, v147
	v_add_f32_e32 v160, 0, v160
	v_add_f32_e32 v160, v160, v163
	s_waitcnt lgkmcnt(1)
	v_mul_f32_e32 v163, v187, v153
	v_fmac_f32_e32 v163, v186, v152
	v_fmac_f32_e32 v163, v180, v154
	v_fmac_f32_e32 v163, v181, v155
	v_add_f32_e32 v160, v160, v163
	s_waitcnt lgkmcnt(0)
	v_mul_f32_e32 v163, v189, v157
	v_fmac_f32_e32 v163, v188, v156
	v_fmac_f32_e32 v163, v184, v158
	v_fmac_f32_e32 v163, v185, v159
	v_add_f32_e32 v160, v160, v163
	s_nop 1
	v_add_f32_dpp v160, v160, v160 quad_perm:[1,0,3,2] row_mask:0xf bank_mask:0xf bound_ctrl:1
	s_nop 1
	v_add_f32_dpp v160, v160, v160 quad_perm:[2,3,0,1] row_mask:0xf bank_mask:0xf bound_ctrl:1
	s_nop 1
	v_add_f32_dpp v160, v160, v160 row_half_mirror row_mask:0xf bank_mask:0xf bound_ctrl:1
	s_nop 1
	v_add_f32_dpp v160, v160, v160 row_mirror row_mask:0xf bank_mask:0xf bound_ctrl:1
	s_nop 0
	v_readlane_b32 s71, v160, 0
	v_readlane_b32 s73, v160, 16
	v_readlane_b32 s72, v160, 32
	v_readlane_b32 s74, v160, 48
	s_and_saveexec_b64 s[22:23], vcc
	s_cbranch_execz .LBB0_103
	v_mov_b32_e32 v160, s58
	v_mov_b32_e32 v163, s59
	v_add_f32_e32 v160, s0, v160
	v_add_f32_e32 v163, s1, v163
	v_add_f32_e32 v160, v160, v163
	v_mov_b32_e32 v163, s61
	v_mov_b32_e32 v174, s27
	v_add_f32_e32 v163, s96, v163
	v_add_f32_e32 v174, s60, v174
	v_add_f32_e32 v163, v163, v174
	v_mov_b32_e32 v174, s35
	v_mov_b32_e32 v175, s46
	v_add_f32_e32 v174, s33, v174
	v_add_f32_e32 v175, s34, v175
	v_add_f32_e32 v174, v174, v175
	v_mov_b32_e32 v175, s49
	v_mov_b32_e32 v176, s50
	v_add_f32_e32 v175, s47, v175
	v_add_f32_e32 v176, s48, v176
	v_cndmask_b32_e64 v160, v160, v163, s[40:41]
	v_add_f32_e32 v175, v175, v176
	v_cndmask_b32_e64 v160, v160, v174, s[42:43]
	v_cndmask_b32_e64 v160, v160, v175, s[44:45]
	s_and_saveexec_b64 s[0:1], s[38:39]
	s_xor_b64 s[58:59], exec, s[0:1]
	s_cbranch_execz .LBB0_107
; template <bool GATES>
; DI void rmsnorm_rows(const float* X, const float* g, bf16_t* U, const float* Wg, const float* b_i, const float* b_f, float* LI, float* LF) {
;     ...
;             if (lane < 8) {
;                 const int b = row >> 11, s = row & 2047, hh = lane & 3;
;                 if (lane < 4) LI[(size_t)(b * 4 + hh) * S_ + s] = val + b_i[hh];
;                 else { const float xx = val + b_f[hh]; LF[(size_t)(b * 4 + hh) * S_ + s] = fminf(xx, 0.f) - log1pf(__expf(-fabsf(xx))); }
	v_mov_b32_e32 v163, s53
	v_mov_b32_e32 v174, s36
	v_add_f32_e32 v163, s51, v163
	v_add_f32_e32 v174, s52, v174
	v_readlane_b32 s0, v245, 21
	v_add_f32_e32 v163, v163, v174
	v_readlane_b32 s1, v245, 22
	v_mov_b32_e32 v174, s65
	v_mov_b32_e32 v175, s66
	v_cndmask_b32_e64 v160, v160, v163, s[0:1]
	v_add_f32_e32 v174, s37, v174
	v_add_f32_e32 v175, s64, v175
	v_readlane_b32 s0, v245, 23
	v_add_f32_e32 v174, v174, v175
	v_mov_b32_e32 v175, s69
	v_mov_b32_e32 v176, s70
	v_readlane_b32 s1, v245, 24
	v_add_f32_e32 v175, s67, v175
	v_add_f32_e32 v176, s68, v176
	v_cndmask_b32_e64 v160, v160, v174, s[0:1]
	v_readlane_b32 s0, v245, 25
	v_add_f32_e32 v175, v175, v176
	v_mov_b32_e32 v176, s73
	v_mov_b32_e32 v177, s74
	v_readlane_b32 s1, v245, 26
	v_add_f32_e32 v176, s71, v176
	v_add_f32_e32 v177, s72, v177
	v_cndmask_b32_e64 v160, v160, v175, s[0:1]
	v_readlane_b32 s0, v245, 27
	v_add_f32_e32 v176, v176, v177
	v_readlane_b32 s1, v245, 28
	s_nop 1
	v_cndmask_b32_e64 v160, v160, v176, s[0:1]
	s_mov_b32 s0, 0xbfb8aa3b
	v_add_f32_e32 v163, v160, v242
	v_min_f32_e32 v160, 0, v163
	v_mul_f32_e64 v163, |v163|, s0
	v_exp_f32_e32 v174, v163
	s_mov_b32 s0, 0x3f2aaaab
	v_add_f32_e32 v163, 1.0, v174
	v_add_f32_e32 v175, -1.0, v163
	v_sub_f32_e32 v176, v175, v163
	v_add_f32_e32 v176, 1.0, v176
	v_sub_f32_e32 v175, v174, v175
	v_add_f32_e32 v175, v175, v176
	v_frexp_mant_f32_e32 v176, v163
	v_cmp_gt_f32_e64 s[0:1], s0, v176
	v_cvt_f64_f32_e32 v[176:177], v163
	v_frexp_exp_i32_f64_e32 v176, v[176:177]
	v_subbrev_co_u32_e64 v184, s[0:1], 0, v176, s[0:1]
	v_sub_u32_e32 v176, 0, v184
	v_ldexp_f32 v163, v163, v176
	v_ldexp_f32 v175, v175, v176
	v_add_f32_e32 v176, -1.0, v163
	v_add_f32_e32 v177, 1.0, v176
	v_sub_f32_e32 v177, v163, v177
	v_add_f32_e32 v178, v175, v177
	v_add_f32_e32 v177, 1.0, v163
	v_add_f32_e32 v179, -1.0, v177
	v_sub_f32_e32 v163, v163, v179
	v_add_f32_e32 v163, v175, v163
	v_add_f32_e32 v175, v177, v163
	v_rcp_f32_e32 v185, v175
	v_sub_f32_e32 v177, v175, v177
	v_sub_f32_e32 v163, v163, v177
	v_add_f32_e32 v177, v176, v178
	v_sub_f32_e32 v176, v177, v176
	v_mul_f32_e32 v187, v177, v185
	v_sub_f32_e32 v186, v178, v176
	v_mul_f32_e32 v178, v175, v187
	v_fma_f32 v180, v187, v175, -v178
	v_fmac_f32_e32 v180, v187, v163
	v_add_f32_e32 v176, v178, v180
	v_sub_f32_e32 v179, v177, v176
	v_pk_add_f32 v[182:183], v[176:177], v[178:179] neg_lo:[0,1] neg_hi:[0,1]
	v_mov_b32_e32 v181, v176
	v_pk_add_f32 v[176:177], v[182:183], v[180:181] neg_lo:[0,1] neg_hi:[0,1]
	s_mov_b32 s0, 0x3f317218
	v_add_f32_e32 v177, v186, v177
	v_add_f32_e32 v176, v176, v177
	v_add_f32_e32 v177, v179, v176
	v_mul_f32_e32 v186, v185, v177
	v_mul_f32_e32 v178, v175, v186
	v_fma_f32 v180, v186, v175, -v178
	v_fmac_f32_e32 v180, v186, v163
	v_sub_f32_e32 v163, v179, v177
	v_add_f32_e32 v163, v176, v163
	v_add_f32_e32 v176, v178, v180
	v_sub_f32_e32 v179, v177, v176
	v_pk_add_f32 v[182:183], v[176:177], v[178:179] neg_lo:[0,1] neg_hi:[0,1]
	v_mov_b32_e32 v181, v176
	v_pk_add_f32 v[176:177], v[182:183], v[180:181] neg_lo:[0,1] neg_hi:[0,1]
	v_add_f32_e32 v175, v187, v186
	v_add_f32_e32 v163, v163, v177
	v_add_f32_e32 v163, v176, v163
	v_add_f32_e32 v163, v179, v163
	v_sub_f32_e32 v176, v175, v187
	v_mul_f32_e32 v163, v185, v163
	v_sub_f32_e32 v176, v186, v176
	v_add_f32_e32 v177, v176, v163
	v_add_f32_e32 v178, v175, v177
	v_cvt_f32_i32_e32 v176, v184
	v_mul_f32_e32 v180, v178, v178
	v_fmamk_f32 v163, v180, 0x3e9b6dac, v190
	v_sub_f32_e32 v175, v178, v175
	v_fmaak_f32 v163, v180, v163, 0x3f2aaada
	v_sub_f32_e32 v175, v177, v175
	v_mul_f32_e32 v177, v178, v180
	v_pk_mul_f32 v[180:181], v[176:177], v[162:163]
	v_ldexp_f32 v179, v178, 1
	v_fma_f32 v178, v176, s0, -v180
	v_fmac_f32_e32 v178, 0xb102e308, v176
	v_pk_add_f32 v[176:177], v[180:181], v[178:179]
	v_ldexp_f32 v175, v175, 1
	v_sub_f32_e32 v163, v177, v179
	v_sub_f32_e32 v163, v181, v163
	v_add_f32_e32 v183, v175, v163
	v_mov_b32_e32 v182, v180
	v_pk_add_f32 v[180:181], v[176:177], v[180:181] neg_lo:[0,1] neg_hi:[0,1]
	v_pk_add_f32 v[184:185], v[176:177], v[182:183]
	v_mov_b32_e32 v179, v176
	v_mov_b32_e32 v181, v185
	v_pk_add_f32 v[186:187], v[178:179], v[180:181] neg_lo:[0,1] neg_hi:[0,1]
	v_pk_add_f32 v[178:179], v[178:179], v[180:181]
	v_mov_b32_e32 v182, v183
	v_pk_add_f32 v[180:181], v[178:179], v[176:177] op_sel:[1,0] op_sel_hi:[0,1] neg_lo:[0,1] neg_hi:[0,1]
	v_pk_add_f32 v[188:189], v[184:185], v[180:181] op_sel_hi:[1,0] neg_lo:[0,1] neg_hi:[0,1]
	v_mov_b32_e32 v184, v185
	v_mov_b32_e32 v185, v179
	v_pk_mov_b32 v[180:181], v[176:177], v[180:181] op_sel:[1,0]
	v_mov_b32_e32 v183, v176
	v_pk_add_f32 v[180:181], v[184:185], v[180:181] neg_lo:[0,1] neg_hi:[0,1]
	v_mov_b32_e32 v188, v186
	v_pk_add_f32 v[176:177], v[182:183], v[180:181] neg_lo:[0,1] neg_hi:[0,1]
	v_mov_b32_e32 v187, v179
	v_pk_add_f32 v[180:181], v[188:189], v[176:177]
	s_mov_b32 s0, 0x7f800000
	v_pk_add_f32 v[182:183], v[180:181], v[180:181] op_sel:[0,1] op_sel_hi:[1,0]
	v_cmp_neq_f32_e64 s[0:1], s0, v174
	v_pk_add_f32 v[178:179], v[178:179], v[182:183] op_sel:[1,0] op_sel_hi:[0,1]
	v_mov_b32_e32 v181, v178
	v_pk_add_f32 v[184:185], v[180:181], v[186:187] neg_lo:[0,1] neg_hi:[0,1]
	v_mov_b32_e32 v177, v182
	v_sub_f32_e32 v163, v180, v184
	v_pk_add_f32 v[176:177], v[176:177], v[184:185] neg_lo:[0,1] neg_hi:[0,1]
	v_sub_f32_e32 v163, v186, v163
	v_add_f32_e32 v163, v176, v163
	v_add_f32_e32 v163, v163, v177
	v_add_f32_e32 v163, v178, v163
	v_cndmask_b32_e64 v163, v195, v163, s[0:1]
	v_cmp_ngt_f32_e64 s[0:1], -1.0, v174
	s_nop 1
	v_cndmask_b32_e64 v163, v196, v163, s[0:1]
	v_cmp_neq_f32_e64 s[0:1], -1.0, v174
	s_nop 1
	v_cndmask_b32_e64 v163, v197, v163, s[0:1]
	s_mov_b32 s0, 0x33800000
	v_cmp_lt_f32_e64 s[0:1], |v174|, s0
	s_nop 1
	v_cndmask_b32_e64 v163, v163, v174, s[0:1]
	v_sub_f32_e32 v163, v160, v163
.LBB0_107:
	s_or_saveexec_b64 s[0:1], s[58:59]
	v_mov_b64_e32 v[174:175], 0x2000000
	s_xor_b64 exec, exec, s[0:1]
	s_cbranch_execz .LBB0_102
	v_mov_b64_e32 v[174:175], 0x1f00000
	v_add_f32_e32 v163, v160, v243
	s_branch .LBB0_102

; DI int opq(int x) { asm volatile("" : "+v"(x)); return x; }
; DI void conv0_phase(const bf16_t* X, const float* w, const float* bias, bf16_t* Y) {
;     const int gt = blockIdx.x * 512 + opq(threadIdx.x), stride = gridDim.x * 512;
;     const int c0 = (gt & 255) * 8;
;     float w0[8], w1[8], w2[8], w3[8], bb[8];
; #pragma unroll
;     for (int e = 0; e < 8; ++e) { w0[e] = w[c0 + e]; w1[e] = w[2048 + c0 + e]; w2[e] = w[4096 + c0 + e]; w3[e] = w[6144 + c0 + e]; bb[e] = bias[c0 + e]; }
;     const int total = (T_ / 16) * 256;
;     u32x4 nx[19];
;     if (gt < total) {
;         const int t0 = (gt >> 8) * 16; const bool first = (t0 & 2047) == 0;
; #pragma unroll
;         for (int r = 0; r < 19; ++r) { const int t = (first && r < 3) ? t0 : t0 - 3 + r; nx[r] = *(const u32x4*)(X + (size_t)t * 2048 + c0); }
;     }
.LBB0_247:
	v_mov_b32_e32 v0, v192
	s_nop 0
	v_add_u32_e32 v200, s47, v0
	v_cmp_gt_i32_e32 vcc, s56, v200
	s_and_saveexec_b64 s[28:29], vcc
	s_cbranch_execz .LBB0_252
	v_lshlrev_b32_e32 v0, 3, v0
	v_and_b32_e32 v35, 0x7f8, v0
	v_readlane_b32 s60, v246, 53
	v_lshlrev_b32_e32 v194, 2, v35
	v_readlane_b32 s68, v246, 61
	v_readlane_b32 s69, v246, 62
	s_mov_b64 s[0:1], 0x2000
	v_ashrrev_i32_e32 v42, 4, v200
	v_lshl_add_u64 v[8:9], s[68:69], 0, v[194:195]
	v_add_co_u32_e32 v32, vcc, 0x2000, v8
	v_lshl_add_u64 v[0:1], v[8:9], 0, s[0:1]
	s_nop 0
	v_addc_co_u32_e32 v33, vcc, 0, v9, vcc
	v_add_co_u32_e32 v10, vcc, 0x4000, v8
	s_mov_b64 s[0:1], 0x4000
	s_nop 0
	v_addc_co_u32_e32 v11, vcc, 0, v9, vcc
	v_add_co_u32_e32 v12, vcc, 0x6000, v8
	v_and_b32_e32 v34, -16, v42
	s_nop 0
	v_addc_co_u32_e32 v13, vcc, 0, v9, vcc
	v_and_b32_e32 v38, 0x7f00, v200
	v_lshl_add_u64 v[4:5], v[8:9], 0, s[0:1]
	s_mov_b64 s[0:1], 0x6000
	v_add_u32_e32 v39, -3, v34
	v_cmp_ne_u32_e32 vcc, 0, v38
	v_readlane_b32 s70, v246, 63
	v_readlane_b32 s71, v245, 0
	v_lshl_add_u64 v[36:37], v[8:9], 0, s[0:1]
	global_load_dwordx4 v[0:3], v[0:1], off offset:16
	s_nop 0
	global_load_dwordx4 v[4:7], v[4:5], off offset:16
	s_nop 0
	global_load_dwordx4 v[8:11], v[10:11], off
	s_nop 0
	global_load_dwordx4 v[12:15], v[12:13], off
	s_nop 0
	global_load_dwordx4 v[16:19], v194, s[68:69] offset:16
	global_load_dwordx4 v[20:23], v194, s[70:71] offset:16
	global_load_dwordx4 v[24:27], v194, s[68:69]
	global_load_dwordx4 v[28:31], v194, s[70:71]
	v_lshlrev_b32_e32 v194, 1, v35
	v_cndmask_b32_e32 v38, v34, v39, vcc
	v_add_u32_e32 v35, -2, v34
	v_ashrrev_i32_e32 v39, 31, v38
	v_cndmask_b32_e32 v40, v34, v35, vcc
	v_lshl_add_u64 v[196:197], s[86:87], 0, v[194:195]
	v_lshlrev_b64 v[38:39], 12, v[38:39]
	v_ashrrev_i32_e32 v41, 31, v40
	v_lshl_add_u64 v[38:39], v[196:197], 0, v[38:39]
	v_lshlrev_b64 v[40:41], 12, v[40:41]
	v_lshl_add_u64 v[40:41], v[196:197], 0, v[40:41]
	global_load_dwordx4 v[184:187], v[38:39], off
	global_load_dwordx4 v[180:183], v[40:41], off
	v_subbrev_co_u32_e32 v38, vcc, 0, v34, vcc
	v_ashrrev_i32_e32 v39, 31, v38
	v_lshlrev_b64 v[38:39], 12, v[38:39]
	v_ashrrev_i32_e32 v35, 31, v34
	v_lshl_add_u64 v[38:39], v[196:197], 0, v[38:39]
	v_lshlrev_b64 v[40:41], 12, v[34:35]
	v_lshl_add_u64 v[40:41], v[196:197], 0, v[40:41]
	global_load_dwordx4 v[188:191], v[38:39], off
	global_load_dwordx4 v[176:179], v[40:41], off
	v_or_b32_e32 v38, 1, v34
	v_ashrrev_i32_e32 v39, 31, v38
	v_or_b32_e32 v40, 2, v34
	v_lshlrev_b64 v[38:39], 12, v[38:39]
	v_ashrrev_i32_e32 v41, 31, v40
	v_lshl_add_u64 v[38:39], v[196:197], 0, v[38:39]
	v_lshlrev_b64 v[40:41], 12, v[40:41]
	v_lshl_add_u64 v[40:41], v[196:197], 0, v[40:41]
	global_load_dwordx4 v[172:175], v[38:39], off
	global_load_dwordx4 v[168:171], v[40:41], off
	v_or_b32_e32 v38, 3, v34
	v_ashrrev_i32_e32 v39, 31, v38
	v_or_b32_e32 v40, 4, v34
	v_lshlrev_b64 v[38:39], 12, v[38:39]
	v_ashrrev_i32_e32 v41, 31, v40
	v_lshl_add_u64 v[38:39], v[196:197], 0, v[38:39]
	v_lshlrev_b64 v[40:41], 12, v[40:41]
	v_lshl_add_u64 v[40:41], v[196:197], 0, v[40:41]
	global_load_dwordx4 v[164:167], v[38:39], off
	global_load_dwordx4 v[160:163], v[40:41], off
	v_or_b32_e32 v38, 5, v34
	v_ashrrev_i32_e32 v39, 31, v38
	v_or_b32_e32 v40, 6, v34
	v_lshlrev_b64 v[38:39], 12, v[38:39]
	v_ashrrev_i32_e32 v41, 31, v40
	v_lshl_add_u64 v[38:39], v[196:197], 0, v[38:39]
	v_lshlrev_b64 v[40:41], 12, v[40:41]
	v_lshl_add_u64 v[40:41], v[196:197], 0, v[40:41]
	global_load_dwordx4 v[156:159], v[38:39], off
	global_load_dwordx4 v[152:155], v[40:41], off
	v_or_b32_e32 v38, 7, v34
	v_ashrrev_i32_e32 v39, 31, v38
	v_or_b32_e32 v40, 8, v34
	v_lshlrev_b64 v[38:39], 12, v[38:39]
	v_ashrrev_i32_e32 v41, 31, v40
	v_lshl_add_u64 v[38:39], v[196:197], 0, v[38:39]
	v_lshlrev_b64 v[40:41], 12, v[40:41]
	v_lshl_add_u64 v[40:41], v[196:197], 0, v[40:41]
	global_load_dwordx4 v[148:151], v[38:39], off
	global_load_dwordx4 v[144:147], v[40:41], off
	v_or_b32_e32 v38, 9, v34
	v_ashrrev_i32_e32 v39, 31, v38
	v_or_b32_e32 v40, 10, v34
	v_lshlrev_b64 v[38:39], 12, v[38:39]
	v_ashrrev_i32_e32 v41, 31, v40
	v_lshl_add_u64 v[38:39], v[196:197], 0, v[38:39]
	v_lshlrev_b64 v[40:41], 12, v[40:41]
	v_lshl_add_u64 v[40:41], v[196:197], 0, v[40:41]
	global_load_dwordx4 v[140:143], v[38:39], off
	global_load_dwordx4 v[136:139], v[40:41], off
	v_or_b32_e32 v38, 11, v34
	v_ashrrev_i32_e32 v39, 31, v38
	v_or_b32_e32 v40, 12, v34
	v_lshlrev_b64 v[38:39], 12, v[38:39]
	v_ashrrev_i32_e32 v41, 31, v40
	v_lshl_add_u64 v[38:39], v[196:197], 0, v[38:39]
	v_lshlrev_b64 v[40:41], 12, v[40:41]
	v_lshl_add_u64 v[40:41], v[196:197], 0, v[40:41]
	global_load_dwordx4 v[132:135], v[38:39], off
	global_load_dwordx4 v[128:131], v[40:41], off
	v_or_b32_e32 v38, 13, v34
	v_or_b32_e32 v34, 14, v34
	v_ashrrev_i32_e32 v39, 31, v38
	v_ashrrev_i32_e32 v35, 31, v34
	v_lshlrev_b64 v[38:39], 12, v[38:39]
	v_lshlrev_b64 v[34:35], 12, v[34:35]
	v_lshl_add_u64 v[38:39], v[196:197], 0, v[38:39]
	v_lshl_add_u64 v[34:35], v[196:197], 0, v[34:35]
	global_load_dwordx4 v[124:127], v[38:39], off
	global_load_dwordx4 v[120:123], v[34:35], off
	v_or_b32_e32 v34, 15, v42
	v_ashrrev_i32_e32 v35, 31, v34
	v_lshlrev_b64 v[34:35], 12, v[34:35]
	v_lshl_add_u64 v[34:35], v[196:197], 0, v[34:35]
	global_load_dwordx4 v[72:75], v[34:35], off
	s_nop 0
	global_load_dwordx4 v[32:35], v[32:33], off
	s_nop 0
	global_load_dwordx4 v[36:39], v[36:37], off offset:16
	v_lshl_add_u64 v[198:199], s[40:41], 0, v[194:195]
	s_waitcnt vmcnt(20)
	v_mov_b64_e32 v[40:41], v[184:185]
	s_waitcnt vmcnt(19)
; DI float silu_(float x) { return x * __builtin_amdgcn_rcpf(1.f + __expf(-x)); }
; DI void conv0_phase(const bf16_t* X, const float* w, const float* bias, bf16_t* Y) {
;     ...
;         for (int r = 0; r < 19; ++r) { const int t = (first && r < 3) ? t0 : t0 - 3 + r; nx[r] = *(const u32x4*)(X + (size_t)t * 2048 + c0); }
;     }
;     for (int it = gt; it < total; it += stride) {
;         const int t0 = (it >> 8) * 16; const bool first = (t0 & 2047) == 0;
;         u32x4 cu[19];
; #pragma unroll
;         for (int r = 0; r < 19; ++r) cu[r] = nx[r];
;         if (it + stride < total) {
;             const int t1 = ((it + stride) >> 8) * 16; const bool f1 = (t1 & 2047) == 0;
; #pragma unroll
;             for (int r = 0; r < 19; ++r) { const int t = (f1 && r < 3) ? t1 : t1 - 3 + r; nx[r] = *(const u32x4*)(X + (size_t)t * 2048 + c0); }
;         }
;         float p3[8], p2[8], p1[8];
;         unpack8(cu[0], p3); unpack8(cu[1], p2); unpack8(cu[2], p1);
;         if (first) {
; #pragma unroll
;             for (int e = 0; e < 8; ++e) { p3[e] = 0.f; p2[e] = 0.f; p1[e] = 0.f; }
;         }
; #pragma unroll
;         for (int r = 0; r < 16; ++r) {
;             float cur[8], y[8];
;             unpack8(cu[3 + r], cur);
; #pragma unroll
;             for (int e = 0; e < 8; ++e) { const float v = bb[e] + w0[e] * p3[e] + w1[e] * p2[e] + w2[e] * p1[e] + w3[e] * cur[e]; y[e] = silu_(v); p3[e] = p2[e]; p2[e] = p1[e]; p1[e] = cur[e]; }
	v_mov_b64_e32 v[44:45], v[180:181]
	s_mov_b64 s[30:31], 0
	v_mov_b64_e32 v[42:43], v[186:187]
	v_mov_b64_e32 v[46:47], v[182:183]
	v_readlane_b32 s61, v246, 54
	v_readlane_b32 s62, v246, 55
	v_readlane_b32 s63, v246, 56
	v_readlane_b32 s64, v246, 57
	s_waitcnt vmcnt(18)
	v_mov_b64_e32 v[48:49], v[188:189]
	s_waitcnt vmcnt(17)
	v_mov_b64_e32 v[52:53], v[176:177]
	v_mov_b64_e32 v[50:51], v[190:191]
	v_mov_b64_e32 v[54:55], v[178:179]
	v_readlane_b32 s65, v246, 58
	v_readlane_b32 s66, v246, 59
	v_readlane_b32 s67, v246, 60
	v_readlane_b32 s72, v245, 1
	v_readlane_b32 s73, v245, 2
	s_waitcnt vmcnt(16)
	v_mov_b64_e32 v[56:57], v[172:173]
	s_waitcnt vmcnt(15)
	v_mov_b64_e32 v[60:61], v[168:169]
	v_mov_b64_e32 v[58:59], v[174:175]
	v_mov_b64_e32 v[62:63], v[170:171]
	v_readlane_b32 s74, v245, 3
	v_readlane_b32 s75, v245, 4
	s_waitcnt vmcnt(14)
	v_mov_b64_e32 v[64:65], v[164:165]
	s_waitcnt vmcnt(13)
	v_mov_b64_e32 v[68:69], v[160:161]
	v_mov_b64_e32 v[66:67], v[166:167]
	v_mov_b64_e32 v[70:71], v[162:163]
	s_waitcnt vmcnt(12)
	v_mov_b64_e32 v[76:77], v[156:157]
	s_waitcnt vmcnt(11)
	v_mov_b64_e32 v[80:81], v[152:153]
	v_mov_b64_e32 v[78:79], v[158:159]
	v_mov_b64_e32 v[82:83], v[154:155]
	s_waitcnt vmcnt(10)
	v_mov_b64_e32 v[84:85], v[148:149]
	s_waitcnt vmcnt(9)
	v_mov_b64_e32 v[88:89], v[144:145]
	v_mov_b64_e32 v[86:87], v[150:151]
	v_mov_b64_e32 v[90:91], v[146:147]
	s_waitcnt vmcnt(8)
	v_mov_b64_e32 v[92:93], v[140:141]
	s_waitcnt vmcnt(7)
	v_mov_b64_e32 v[96:97], v[136:137]
	v_mov_b64_e32 v[94:95], v[142:143]
	v_mov_b64_e32 v[98:99], v[138:139]
	s_waitcnt vmcnt(6)
	v_mov_b64_e32 v[100:101], v[132:133]
	s_waitcnt vmcnt(5)
	v_mov_b64_e32 v[104:105], v[128:129]
	v_mov_b64_e32 v[102:103], v[134:135]
	v_mov_b64_e32 v[106:107], v[130:131]
	s_waitcnt vmcnt(4)
	v_mov_b64_e32 v[108:109], v[124:125]
	s_waitcnt vmcnt(3)
	v_mov_b64_e32 v[112:113], v[120:121]
	v_mov_b64_e32 v[110:111], v[126:127]
	v_mov_b64_e32 v[114:115], v[122:123]
	s_waitcnt vmcnt(2)
	v_mov_b64_e32 v[118:119], v[74:75]
	v_mov_b64_e32 v[116:117], v[72:73]
	s_waitcnt vmcnt(0)
	s_branch .LBB0_250
.LBB0_249:
	s_or_b64 exec, exec, s[0:1]
	v_and_b32_e32 v201, 0x7f00, v200
	v_cmp_eq_u32_e32 vcc, 0, v201
	v_lshlrev_b32_e32 v201, 16, v184
	v_and_b32_e32 v184, 0xffff0000, v184
	v_lshlrev_b32_e32 v202, 16, v185
	v_lshlrev_b32_e32 v216, 16, v180
	v_and_b32_e32 v180, 0xffff0000, v180
	v_lshlrev_b32_e32 v217, 16, v183
	v_cndmask_b32_e64 v213, v184, 0, vcc
	v_cndmask_b32_e64 v212, v201, 0, vcc
	v_and_b32_e32 v185, 0xffff0000, v185
	v_lshlrev_b32_e32 v204, 16, v187
	v_and_b32_e32 v187, 0xffff0000, v187
	v_lshlrev_b32_e32 v207, 16, v182
	v_and_b32_e32 v205, 0xffff0000, v182
	v_lshlrev_b32_e32 v219, 16, v188
	v_and_b32_e32 v220, 0xffff0000, v188
	v_lshlrev_b32_e32 v221, 16, v190
	v_and_b32_e32 v190, 0xffff0000, v190
	v_lshlrev_b32_e32 v222, 16, v191
	v_and_b32_e32 v191, 0xffff0000, v191
	v_cndmask_b32_e64 v182, v202, 0, vcc
	v_cndmask_b32_e64 v202, v217, 0, vcc
	v_cndmask_b32_e64 v217, v180, 0, vcc
	v_cndmask_b32_e64 v216, v216, 0, vcc
	v_pk_fma_f32 v[212:213], v[24:25], v[212:213], v[28:29]
	v_lshlrev_b32_e32 v206, 16, v181
	v_and_b32_e32 v181, 0xffff0000, v181
	v_and_b32_e32 v218, 0xffff0000, v183
	v_cndmask_b32_e64 v209, v187, 0, vcc
	v_cndmask_b32_e64 v183, v185, 0, vcc
	v_cndmask_b32_e64 v185, v191, 0, vcc
	v_cndmask_b32_e64 v187, v190, 0, vcc
	v_cndmask_b32_e64 v191, v220, 0, vcc
	v_cndmask_b32_e64 v190, v219, 0, vcc
	v_pk_fma_f32 v[212:213], v[32:33], v[216:217], v[212:213]
	v_cndmask_b32_e64 v208, v204, 0, vcc
	v_cndmask_b32_e64 v204, v207, 0, vcc
	v_cndmask_b32_e64 v207, v181, 0, vcc
	v_lshlrev_b32_e32 v180, 16, v176
	v_and_b32_e32 v181, 0xffff0000, v176
	v_pk_fma_f32 v[212:213], v[8:9], v[190:191], v[212:213]
	v_lshlrev_b32_e32 v203, 16, v186
	v_pk_fma_f32 v[212:213], v[12:13], v[180:181], v[212:213]
	v_cndmask_b32_e64 v210, v203, 0, vcc
	v_mul_f32_e32 v176, 0xbfb8aa3b, v212
	v_exp_f32_e32 v176, v176
	v_cndmask_b32_e64 v203, v218, 0, vcc
	v_lshlrev_b32_e32 v188, 16, v189
	v_and_b32_e32 v189, 0xffff0000, v189
	v_add_f32_e32 v176, 1.0, v176
	v_rcp_f32_e32 v218, v176
	v_mul_f32_e32 v176, 0xbfb8aa3b, v213
	v_exp_f32_e32 v176, v176
	v_cndmask_b32_e64 v206, v206, 0, vcc
	v_pk_fma_f32 v[182:183], v[26:27], v[182:183], v[30:31]
	v_cndmask_b32_e64 v189, v189, 0, vcc
	v_cndmask_b32_e64 v188, v188, 0, vcc
	v_add_f32_e32 v176, 1.0, v176
	v_pk_fma_f32 v[182:183], v[34:35], v[206:207], v[182:183]
	v_rcp_f32_e32 v219, v176
	v_lshlrev_b32_e32 v176, 16, v177
	v_and_b32_e32 v177, 0xffff0000, v177
	v_pk_fma_f32 v[182:183], v[10:11], v[188:189], v[182:183]
	v_pk_mul_f32 v[212:213], v[212:213], v[218:219]
	v_pk_fma_f32 v[182:183], v[14:15], v[176:177], v[182:183]
	v_and_b32_e32 v186, 0xffff0000, v186
	v_mul_f32_e32 v201, 0xbfb8aa3b, v182
	v_exp_f32_e32 v201, v201
	v_cndmask_b32_e64 v211, v186, 0, vcc
	v_cndmask_b32_e64 v205, v205, 0, vcc
	v_pk_fma_f32 v[210:211], v[16:17], v[210:211], v[20:21]
	v_add_f32_e32 v201, 1.0, v201
	v_rcp_f32_e32 v218, v201
	v_mul_f32_e32 v201, 0xbfb8aa3b, v183
	v_exp_f32_e32 v201, v201
	v_cndmask_b32_e64 v186, v221, 0, vcc
	v_pk_fma_f32 v[210:211], v[0:1], v[204:205], v[210:211]
	v_pk_fma_f32 v[208:209], v[18:19], v[208:209], v[22:23]
	v_add_f32_e32 v201, 1.0, v201
	v_rcp_f32_e32 v219, v201
	v_pk_fma_f32 v[210:211], v[4:5], v[186:187], v[210:211]
	v_cndmask_b32_e64 v184, v222, 0, vcc
	v_pk_fma_f32 v[208:209], v[2:3], v[202:203], v[208:209]
	v_pk_mul_f32 v[218:219], v[182:183], v[218:219]
	v_lshlrev_b32_e32 v182, 16, v178
	v_and_b32_e32 v183, 0xffff0000, v178
	v_pk_fma_f32 v[210:211], v[36:37], v[182:183], v[210:211]
	v_pk_fma_f32 v[208:209], v[6:7], v[184:185], v[208:209]
; DI float silu_(float x) { return x * __builtin_amdgcn_rcpf(1.f + __expf(-x)); }
; DI u32x4 pack8f(const float (&f)[8]) { u32x4 r; r[0] = pk2(f[0], f[1]); r[1] = pk2(f[2], f[3]); r[2] = pk2(f[4], f[5]); r[3] = pk2(f[6], f[7]); return r; }
; DI void conv0_phase(const bf16_t* X, const float* w, const float* bias, bf16_t* Y) {
;     ...
;         for (int r = 0; r < 16; ++r) {
;             float cur[8], y[8];
;             unpack8(cu[3 + r], cur);
; #pragma unroll
;             for (int e = 0; e < 8; ++e) { const float v = bb[e] + w0[e] * p3[e] + w1[e] * p2[e] + w2[e] * p1[e] + w3[e] * cur[e]; y[e] = silu_(v); p3[e] = p2[e]; p2[e] = p1[e]; p1[e] = cur[e]; }
;             *(u32x4*)(Y + (size_t)(t0 + r) * 2048 + c0) = pack8f(y);
;         }
	v_mul_f32_e32 v178, 0xbfb8aa3b, v210
	v_exp_f32_e32 v178, v178
	v_ashrrev_i32_e32 v215, 4, v200
	v_and_b32_e32 v200, -16, v215
	v_add_f32_e32 v178, 1.0, v178
	v_rcp_f32_e32 v220, v178
	v_mul_f32_e32 v178, 0xbfb8aa3b, v211
	v_exp_f32_e32 v178, v178
	s_nop 0
	v_add_f32_e32 v178, 1.0, v178
	v_rcp_f32_e32 v221, v178
	v_lshlrev_b32_e32 v178, 16, v179
	v_and_b32_e32 v179, 0xffff0000, v179
	v_pk_fma_f32 v[208:209], v[38:39], v[178:179], v[208:209]
	v_pk_mul_f32 v[210:211], v[210:211], v[220:221]
	v_mul_f32_e32 v201, 0xbfb8aa3b, v208
	v_exp_f32_e32 v201, v201
	v_cvt_pk_bf16_f32 v210, v210, v211
	v_add_f32_e32 v201, 1.0, v201
	v_rcp_f32_e32 v220, v201
	v_mul_f32_e32 v201, 0xbfb8aa3b, v209
	v_exp_f32_e32 v201, v201
	s_nop 0
	v_add_f32_e32 v201, 1.0, v201
	v_rcp_f32_e32 v221, v201
	v_ashrrev_i32_e32 v201, 31, v200
	v_pk_mul_f32 v[220:221], v[208:209], v[220:221]
	v_cvt_pk_bf16_f32 v208, v212, v213
	v_lshlrev_b64 v[212:213], 12, v[200:201]
	v_cvt_pk_bf16_f32 v209, v218, v219
	v_cvt_pk_bf16_f32 v211, v220, v221
	v_lshl_add_u64 v[212:213], v[198:199], 0, v[212:213]
	global_store_dwordx4 v[212:213], v[208:211], off
	v_lshlrev_b32_e32 v212, 16, v172
	v_and_b32_e32 v213, 0xffff0000, v172
	v_pk_fma_f32 v[208:209], v[24:25], v[216:217], v[28:29]
	s_nop 0
	v_pk_fma_f32 v[208:209], v[32:33], v[190:191], v[208:209]
	s_nop 0
	v_pk_fma_f32 v[208:209], v[8:9], v[180:181], v[208:209]
	s_nop 0
	v_pk_fma_f32 v[208:209], v[12:13], v[212:213], v[208:209]
	s_nop 0
	v_mul_f32_e32 v172, 0xbfb8aa3b, v208
	v_exp_f32_e32 v172, v172
	s_nop 0
	v_add_f32_e32 v172, 1.0, v172
	v_rcp_f32_e32 v210, v172
	v_mul_f32_e32 v172, 0xbfb8aa3b, v209
	v_exp_f32_e32 v172, v172
	s_nop 0
	v_add_f32_e32 v172, 1.0, v172
	v_rcp_f32_e32 v211, v172
	s_nop 0
	v_pk_mul_f32 v[216:217], v[208:209], v[210:211]
	v_lshlrev_b32_e32 v210, 16, v173
	v_and_b32_e32 v211, 0xffff0000, v173
	v_pk_fma_f32 v[172:173], v[26:27], v[206:207], v[30:31]
	v_lshlrev_b32_e32 v208, 16, v174
	v_pk_fma_f32 v[172:173], v[34:35], v[188:189], v[172:173]
	v_and_b32_e32 v209, 0xffff0000, v174
	v_pk_fma_f32 v[172:173], v[10:11], v[176:177], v[172:173]
	s_nop 0
	v_pk_fma_f32 v[172:173], v[14:15], v[210:211], v[172:173]
	s_nop 0
	v_mul_f32_e32 v201, 0xbfb8aa3b, v172
	v_exp_f32_e32 v201, v201
	s_nop 0
	v_add_f32_e32 v201, 1.0, v201
	v_rcp_f32_e32 v206, v201
	v_mul_f32_e32 v201, 0xbfb8aa3b, v173
	v_exp_f32_e32 v201, v201
	s_nop 0
	v_add_f32_e32 v201, 1.0, v201
	v_rcp_f32_e32 v207, v201
	s_nop 0
	v_pk_mul_f32 v[218:219], v[172:173], v[206:207]
	v_pk_fma_f32 v[172:173], v[16:17], v[204:205], v[20:21]
	v_lshlrev_b32_e32 v206, 16, v175
	v_pk_fma_f32 v[172:173], v[0:1], v[186:187], v[172:173]
	v_and_b32_e32 v207, 0xffff0000, v175
	v_pk_fma_f32 v[172:173], v[4:5], v[182:183], v[172:173]
	s_nop 0
	v_pk_fma_f32 v[172:173], v[36:37], v[208:209], v[172:173]
	s_nop 0
	v_mul_f32_e32 v174, 0xbfb8aa3b, v172
	v_exp_f32_e32 v174, v174
	s_nop 0
	v_add_f32_e32 v174, 1.0, v174
	v_rcp_f32_e32 v204, v174
	v_mul_f32_e32 v174, 0xbfb8aa3b, v173
	v_exp_f32_e32 v174, v174
	s_nop 0
	v_add_f32_e32 v174, 1.0, v174
	v_rcp_f32_e32 v205, v174
	s_nop 0
	v_pk_mul_f32 v[204:205], v[172:173], v[204:205]
	v_pk_fma_f32 v[172:173], v[18:19], v[202:203], v[22:23]
	s_nop 0
	v_pk_fma_f32 v[172:173], v[2:3], v[184:185], v[172:173]
	s_nop 0
	v_pk_fma_f32 v[172:173], v[6:7], v[178:179], v[172:173]
	s_nop 0
	v_pk_fma_f32 v[172:173], v[38:39], v[206:207], v[172:173]
	s_nop 0
	v_mul_f32_e32 v174, 0xbfb8aa3b, v172
	v_mul_f32_e32 v175, 0xbfb8aa3b, v173
	v_exp_f32_e32 v174, v174
	v_exp_f32_e32 v175, v175
	v_add_f32_e32 v174, 1.0, v174
	v_add_f32_e32 v175, 1.0, v175
	v_rcp_f32_e32 v174, v174
	v_rcp_f32_e32 v175, v175
	s_nop 0
	v_pk_mul_f32 v[202:203], v[172:173], v[174:175]
	s_nop 0
	v_cvt_pk_bf16_f32 v175, v202, v203
	v_or_b32_e32 v202, 1, v200
	v_ashrrev_i32_e32 v203, 31, v202
	v_lshlrev_b64 v[202:203], 12, v[202:203]
	v_cvt_pk_bf16_f32 v172, v216, v217
	v_cvt_pk_bf16_f32 v173, v218, v219
	v_cvt_pk_bf16_f32 v174, v204, v205
	v_lshl_add_u64 v[202:203], v[198:199], 0, v[202:203]
	global_store_dwordx4 v[202:203], v[172:175], off
	v_lshlrev_b32_e32 v204, 16, v168
	v_and_b32_e32 v205, 0xffff0000, v168
	v_pk_fma_f32 v[172:173], v[24:25], v[190:191], v[28:29]
	v_lshlrev_b32_e32 v202, 16, v169
	v_pk_fma_f32 v[172:173], v[32:33], v[180:181], v[172:173]
	v_and_b32_e32 v203, 0xffff0000, v169
	v_pk_fma_f32 v[172:173], v[8:9], v[212:213], v[172:173]
	v_lshlrev_b32_e32 v190, 16, v170
	v_pk_fma_f32 v[172:173], v[12:13], v[204:205], v[172:173]
	v_and_b32_e32 v191, 0xffff0000, v170
	v_mul_f32_e32 v168, 0xbfb8aa3b, v172
	v_exp_f32_e32 v168, v168
	s_nop 0
	v_add_f32_e32 v168, 1.0, v168
	v_rcp_f32_e32 v174, v168
	v_mul_f32_e32 v168, 0xbfb8aa3b, v173
	v_exp_f32_e32 v168, v168
	s_nop 0
	v_add_f32_e32 v168, 1.0, v168
	v_rcp_f32_e32 v175, v168
	v_pk_fma_f32 v[168:169], v[26:27], v[188:189], v[30:31]
	v_lshlrev_b32_e32 v188, 16, v171
	v_pk_fma_f32 v[168:169], v[34:35], v[176:177], v[168:169]
	v_pk_mul_f32 v[172:173], v[172:173], v[174:175]
	v_pk_fma_f32 v[168:169], v[10:11], v[210:211], v[168:169]
	v_and_b32_e32 v189, 0xffff0000, v171
	v_pk_fma_f32 v[168:169], v[14:15], v[202:203], v[168:169]
	s_nop 0
	v_mul_f32_e32 v174, 0xbfb8aa3b, v168
	v_mul_f32_e32 v175, 0xbfb8aa3b, v169
	v_exp_f32_e32 v174, v174
	v_exp_f32_e32 v175, v175
	v_add_f32_e32 v174, 1.0, v174
	v_add_f32_e32 v175, 1.0, v175
	v_rcp_f32_e32 v174, v174
	v_rcp_f32_e32 v175, v175
	s_nop 0
	v_pk_mul_f32 v[174:175], v[168:169], v[174:175]
	v_pk_fma_f32 v[168:169], v[16:17], v[186:187], v[20:21]
	s_nop 0
	v_pk_fma_f32 v[168:169], v[0:1], v[182:183], v[168:169]
	s_nop 0
	v_pk_fma_f32 v[168:169], v[4:5], v[208:209], v[168:169]
	s_nop 0
; DI float silu_(float x) { return x * __builtin_amdgcn_rcpf(1.f + __expf(-x)); }
; DI u32x4 pack8f(const float (&f)[8]) { u32x4 r; r[0] = pk2(f[0], f[1]); r[1] = pk2(f[2], f[3]); r[2] = pk2(f[4], f[5]); r[3] = pk2(f[6], f[7]); return r; }
; DI void conv0_phase(const bf16_t* X, const float* w, const float* bias, bf16_t* Y) {
;     ...
;         for (int r = 0; r < 16; ++r) {
;             float cur[8], y[8];
;             unpack8(cu[3 + r], cur);
; #pragma unroll
;             for (int e = 0; e < 8; ++e) { const float v = bb[e] + w0[e] * p3[e] + w1[e] * p2[e] + w2[e] * p1[e] + w3[e] * cur[e]; y[e] = silu_(v); p3[e] = p2[e]; p2[e] = p1[e]; p1[e] = cur[e]; }
;             *(u32x4*)(Y + (size_t)(t0 + r) * 2048 + c0) = pack8f(y);
;         }
	v_pk_fma_f32 v[168:169], v[36:37], v[190:191], v[168:169]
	s_nop 0
	v_mul_f32_e32 v170, 0xbfb8aa3b, v168
	v_exp_f32_e32 v170, v170
	s_nop 0
	v_add_f32_e32 v170, 1.0, v170
	v_rcp_f32_e32 v186, v170
	v_mul_f32_e32 v170, 0xbfb8aa3b, v169
	v_exp_f32_e32 v170, v170
	s_nop 0
	v_add_f32_e32 v170, 1.0, v170
	v_rcp_f32_e32 v187, v170
	s_nop 0
	v_pk_mul_f32 v[186:187], v[168:169], v[186:187]
	v_pk_fma_f32 v[168:169], v[18:19], v[184:185], v[22:23]
	s_nop 0
	v_pk_fma_f32 v[168:169], v[2:3], v[178:179], v[168:169]
	s_nop 0
	v_pk_fma_f32 v[168:169], v[6:7], v[206:207], v[168:169]
	s_nop 0
	v_pk_fma_f32 v[168:169], v[38:39], v[188:189], v[168:169]
	s_nop 0
	v_mul_f32_e32 v170, 0xbfb8aa3b, v168
	v_mul_f32_e32 v171, 0xbfb8aa3b, v169
	v_exp_f32_e32 v170, v170
	v_exp_f32_e32 v171, v171
	v_add_f32_e32 v170, 1.0, v170
	v_add_f32_e32 v171, 1.0, v171
	v_rcp_f32_e32 v170, v170
	v_rcp_f32_e32 v171, v171
	s_nop 0
	v_pk_mul_f32 v[184:185], v[168:169], v[170:171]
	v_cvt_pk_bf16_f32 v168, v172, v173
	v_or_b32_e32 v172, 2, v200
	v_ashrrev_i32_e32 v173, 31, v172
	v_lshlrev_b64 v[172:173], 12, v[172:173]
	v_cvt_pk_bf16_f32 v169, v174, v175
	v_cvt_pk_bf16_f32 v170, v186, v187
	v_cvt_pk_bf16_f32 v171, v184, v185
	v_lshl_add_u64 v[172:173], v[198:199], 0, v[172:173]
	global_store_dwordx4 v[172:173], v[168:171], off
	v_lshlrev_b32_e32 v186, 16, v164
	v_and_b32_e32 v187, 0xffff0000, v164
	v_pk_fma_f32 v[168:169], v[24:25], v[180:181], v[28:29]
	v_lshlrev_b32_e32 v184, 16, v165
	v_pk_fma_f32 v[168:169], v[32:33], v[212:213], v[168:169]
	v_and_b32_e32 v185, 0xffff0000, v165
	v_pk_fma_f32 v[168:169], v[8:9], v[204:205], v[168:169]
	v_lshlrev_b32_e32 v180, 16, v166
	v_pk_fma_f32 v[168:169], v[12:13], v[186:187], v[168:169]
	v_and_b32_e32 v181, 0xffff0000, v166
	v_mul_f32_e32 v164, 0xbfb8aa3b, v168
	v_exp_f32_e32 v164, v164
	v_lshlrev_b32_e32 v174, 16, v167
	v_and_b32_e32 v175, 0xffff0000, v167
	v_add_f32_e32 v164, 1.0, v164
	v_rcp_f32_e32 v170, v164
	v_mul_f32_e32 v164, 0xbfb8aa3b, v169
	v_exp_f32_e32 v164, v164
	s_nop 0
	v_add_f32_e32 v164, 1.0, v164
	v_rcp_f32_e32 v171, v164
	v_pk_fma_f32 v[164:165], v[26:27], v[176:177], v[30:31]
	v_pk_mul_f32 v[168:169], v[168:169], v[170:171]
	v_pk_fma_f32 v[164:165], v[34:35], v[210:211], v[164:165]
	s_nop 0
	v_pk_fma_f32 v[164:165], v[10:11], v[202:203], v[164:165]
	s_nop 0
	v_pk_fma_f32 v[164:165], v[14:15], v[184:185], v[164:165]
	s_nop 0
	v_mul_f32_e32 v170, 0xbfb8aa3b, v164
	v_mul_f32_e32 v171, 0xbfb8aa3b, v165
	v_exp_f32_e32 v170, v170
	v_exp_f32_e32 v171, v171
	v_add_f32_e32 v170, 1.0, v170
	v_add_f32_e32 v171, 1.0, v171
	v_rcp_f32_e32 v170, v170
	v_rcp_f32_e32 v171, v171
	s_nop 0
	v_pk_mul_f32 v[170:171], v[164:165], v[170:171]
	v_pk_fma_f32 v[164:165], v[16:17], v[182:183], v[20:21]
	s_nop 0
	v_pk_fma_f32 v[164:165], v[0:1], v[208:209], v[164:165]
	s_nop 0
	v_pk_fma_f32 v[164:165], v[4:5], v[190:191], v[164:165]
	s_nop 0
	v_pk_fma_f32 v[164:165], v[36:37], v[180:181], v[164:165]
	s_nop 0
	v_mul_f32_e32 v166, 0xbfb8aa3b, v164
	v_exp_f32_e32 v166, v166
	s_nop 0
	v_add_f32_e32 v166, 1.0, v166
	v_rcp_f32_e32 v172, v166
	v_mul_f32_e32 v166, 0xbfb8aa3b, v165
	v_exp_f32_e32 v166, v166
	s_nop 0
	v_add_f32_e32 v166, 1.0, v166
	v_rcp_f32_e32 v173, v166
	s_nop 0
	v_pk_mul_f32 v[172:173], v[164:165], v[172:173]
	v_pk_fma_f32 v[164:165], v[18:19], v[178:179], v[22:23]
	v_lshlrev_b32_e32 v178, 16, v160
	v_pk_fma_f32 v[164:165], v[2:3], v[206:207], v[164:165]
	v_and_b32_e32 v179, 0xffff0000, v160
	v_pk_fma_f32 v[164:165], v[6:7], v[188:189], v[164:165]
	s_nop 0
	v_pk_fma_f32 v[164:165], v[38:39], v[174:175], v[164:165]
	s_nop 0
	v_mul_f32_e32 v166, 0xbfb8aa3b, v164
	v_mul_f32_e32 v167, 0xbfb8aa3b, v165
	v_exp_f32_e32 v166, v166
	v_exp_f32_e32 v167, v167
	v_add_f32_e32 v166, 1.0, v166
	v_add_f32_e32 v167, 1.0, v167
	v_rcp_f32_e32 v166, v166
	v_rcp_f32_e32 v167, v167
	s_nop 0
	v_pk_mul_f32 v[176:177], v[164:165], v[166:167]
	v_cvt_pk_bf16_f32 v164, v168, v169
	v_or_b32_e32 v168, 3, v200
	v_ashrrev_i32_e32 v169, 31, v168
	v_lshlrev_b64 v[168:169], 12, v[168:169]
	v_cvt_pk_bf16_f32 v165, v170, v171
	v_cvt_pk_bf16_f32 v166, v172, v173
	v_cvt_pk_bf16_f32 v167, v176, v177
	v_lshl_add_u64 v[168:169], v[198:199], 0, v[168:169]
	global_store_dwordx4 v[168:169], v[164:167], off
	v_lshlrev_b32_e32 v172, 16, v161
	v_and_b32_e32 v173, 0xffff0000, v161
	v_pk_fma_f32 v[164:165], v[24:25], v[212:213], v[28:29]
	v_lshlrev_b32_e32 v170, 16, v162
	v_pk_fma_f32 v[164:165], v[32:33], v[204:205], v[164:165]
	v_and_b32_e32 v171, 0xffff0000, v162
	v_pk_fma_f32 v[164:165], v[8:9], v[186:187], v[164:165]
	s_nop 0
	v_pk_fma_f32 v[164:165], v[12:13], v[178:179], v[164:165]
	s_nop 0
	v_mul_f32_e32 v160, 0xbfb8aa3b, v164
	v_exp_f32_e32 v160, v160
	s_nop 0
	v_add_f32_e32 v160, 1.0, v160
	v_rcp_f32_e32 v166, v160
	v_mul_f32_e32 v160, 0xbfb8aa3b, v165
	v_exp_f32_e32 v160, v160
	s_nop 0
	v_add_f32_e32 v160, 1.0, v160
	v_rcp_f32_e32 v167, v160
	v_pk_fma_f32 v[160:161], v[26:27], v[210:211], v[30:31]
	v_pk_mul_f32 v[164:165], v[164:165], v[166:167]
	v_pk_fma_f32 v[160:161], v[34:35], v[202:203], v[160:161]
	s_nop 0
	v_pk_fma_f32 v[160:161], v[10:11], v[184:185], v[160:161]
	s_nop 0
	v_pk_fma_f32 v[160:161], v[14:15], v[172:173], v[160:161]
	s_nop 0
	v_mul_f32_e32 v166, 0xbfb8aa3b, v160
	v_mul_f32_e32 v167, 0xbfb8aa3b, v161
	v_exp_f32_e32 v166, v166
	v_exp_f32_e32 v167, v167
	v_add_f32_e32 v166, 1.0, v166
	v_add_f32_e32 v167, 1.0, v167
	v_rcp_f32_e32 v166, v166
	v_rcp_f32_e32 v167, v167
	s_nop 0
	v_pk_mul_f32 v[166:167], v[160:161], v[166:167]
	v_pk_fma_f32 v[160:161], v[16:17], v[208:209], v[20:21]
	s_nop 0
	v_pk_fma_f32 v[160:161], v[0:1], v[190:191], v[160:161]
	s_nop 0
; DI float silu_(float x) { return x * __builtin_amdgcn_rcpf(1.f + __expf(-x)); }
; DI u32x4 pack8f(const float (&f)[8]) { u32x4 r; r[0] = pk2(f[0], f[1]); r[1] = pk2(f[2], f[3]); r[2] = pk2(f[4], f[5]); r[3] = pk2(f[6], f[7]); return r; }
; DI void conv0_phase(const bf16_t* X, const float* w, const float* bias, bf16_t* Y) {
;     ...
;         for (int r = 0; r < 19; ++r) cu[r] = nx[r];
;         if (it + stride < total) {
;             const int t1 = ((it + stride) >> 8) * 16; const bool f1 = (t1 & 2047) == 0;
; #pragma unroll
;             for (int r = 0; r < 19; ++r) { const int t = (f1 && r < 3) ? t1 : t1 - 3 + r; nx[r] = *(const u32x4*)(X + (size_t)t * 2048 + c0); }
;     ...
;         for (int r = 0; r < 16; ++r) {
;             float cur[8], y[8];
;             unpack8(cu[3 + r], cur);
; #pragma unroll
;             for (int e = 0; e < 8; ++e) { const float v = bb[e] + w0[e] * p3[e] + w1[e] * p2[e] + w2[e] * p1[e] + w3[e] * cur[e]; y[e] = silu_(v); p3[e] = p2[e]; p2[e] = p1[e]; p1[e] = cur[e]; }
;             *(u32x4*)(Y + (size_t)(t0 + r) * 2048 + c0) = pack8f(y);
;         }
	v_pk_fma_f32 v[160:161], v[4:5], v[180:181], v[160:161]
	s_nop 0
	v_pk_fma_f32 v[160:161], v[36:37], v[170:171], v[160:161]
	s_nop 0
	v_mul_f32_e32 v162, 0xbfb8aa3b, v160
	v_exp_f32_e32 v162, v162
	s_nop 0
	v_add_f32_e32 v162, 1.0, v162
	v_rcp_f32_e32 v168, v162
	v_mul_f32_e32 v162, 0xbfb8aa3b, v161
	v_exp_f32_e32 v162, v162
	s_nop 0
	v_add_f32_e32 v162, 1.0, v162
	v_rcp_f32_e32 v169, v162
	s_nop 0
	v_pk_mul_f32 v[176:177], v[160:161], v[168:169]
	v_pk_fma_f32 v[160:161], v[18:19], v[206:207], v[22:23]
	v_lshlrev_b32_e32 v168, 16, v163
	v_pk_fma_f32 v[160:161], v[2:3], v[188:189], v[160:161]
	v_and_b32_e32 v169, 0xffff0000, v163
	v_pk_fma_f32 v[160:161], v[6:7], v[174:175], v[160:161]
	s_nop 0
	v_pk_fma_f32 v[160:161], v[38:39], v[168:169], v[160:161]
	s_nop 0
	v_mul_f32_e32 v162, 0xbfb8aa3b, v160
	v_mul_f32_e32 v163, 0xbfb8aa3b, v161
	v_exp_f32_e32 v162, v162
	v_exp_f32_e32 v163, v163
	v_add_f32_e32 v162, 1.0, v162
	v_add_f32_e32 v163, 1.0, v163
	v_rcp_f32_e32 v162, v162
	v_rcp_f32_e32 v163, v163
	s_nop 0
	v_pk_mul_f32 v[182:183], v[160:161], v[162:163]
	v_cvt_pk_bf16_f32 v160, v164, v165
	v_or_b32_e32 v164, 4, v200
	v_ashrrev_i32_e32 v165, 31, v164
	v_lshlrev_b64 v[164:165], 12, v[164:165]
	v_cvt_pk_bf16_f32 v161, v166, v167
	v_cvt_pk_bf16_f32 v162, v176, v177
	v_cvt_pk_bf16_f32 v163, v182, v183
	v_lshl_add_u64 v[164:165], v[198:199], 0, v[164:165]
	global_store_dwordx4 v[164:165], v[160:163], off
	v_lshlrev_b32_e32 v166, 16, v156
	v_and_b32_e32 v167, 0xffff0000, v156
	v_pk_fma_f32 v[160:161], v[24:25], v[204:205], v[28:29]
	v_lshlrev_b32_e32 v164, 16, v157
	v_pk_fma_f32 v[160:161], v[32:33], v[186:187], v[160:161]
	v_and_b32_e32 v165, 0xffff0000, v157
	v_pk_fma_f32 v[160:161], v[8:9], v[178:179], v[160:161]
	s_nop 0
	v_pk_fma_f32 v[160:161], v[12:13], v[166:167], v[160:161]
	s_nop 0
	v_mul_f32_e32 v156, 0xbfb8aa3b, v160
	v_exp_f32_e32 v156, v156
	s_nop 0
	v_add_f32_e32 v156, 1.0, v156
	v_rcp_f32_e32 v162, v156
	v_mul_f32_e32 v156, 0xbfb8aa3b, v161
	v_exp_f32_e32 v156, v156
	s_nop 0
	v_add_f32_e32 v156, 1.0, v156
	v_rcp_f32_e32 v163, v156
	v_pk_fma_f32 v[156:157], v[26:27], v[202:203], v[30:31]
	v_pk_mul_f32 v[176:177], v[160:161], v[162:163]
	v_pk_fma_f32 v[156:157], v[34:35], v[184:185], v[156:157]
	v_lshlrev_b32_e32 v162, 16, v158
	v_pk_fma_f32 v[156:157], v[10:11], v[172:173], v[156:157]
	v_and_b32_e32 v163, 0xffff0000, v158
	v_pk_fma_f32 v[156:157], v[14:15], v[164:165], v[156:157]
	s_nop 0
	v_mul_f32_e32 v160, 0xbfb8aa3b, v156
	v_mul_f32_e32 v161, 0xbfb8aa3b, v157
	v_exp_f32_e32 v160, v160
	v_exp_f32_e32 v161, v161
	v_add_f32_e32 v160, 1.0, v160
	v_add_f32_e32 v161, 1.0, v161
	v_rcp_f32_e32 v160, v160
	v_rcp_f32_e32 v161, v161
	s_nop 0
	v_pk_mul_f32 v[182:183], v[156:157], v[160:161]
	v_pk_fma_f32 v[156:157], v[16:17], v[190:191], v[20:21]
	s_nop 0
	v_pk_fma_f32 v[156:157], v[0:1], v[180:181], v[156:157]
	s_nop 0
	v_pk_fma_f32 v[156:157], v[4:5], v[170:171], v[156:157]
	s_nop 0
	v_pk_fma_f32 v[156:157], v[36:37], v[162:163], v[156:157]
	s_nop 0
	v_mul_f32_e32 v158, 0xbfb8aa3b, v156
	v_exp_f32_e32 v158, v158
	s_nop 0
	v_add_f32_e32 v158, 1.0, v158
	v_rcp_f32_e32 v160, v158
	v_mul_f32_e32 v158, 0xbfb8aa3b, v157
	v_exp_f32_e32 v158, v158
	s_nop 0
	v_add_f32_e32 v158, 1.0, v158
	v_rcp_f32_e32 v161, v158
	s_nop 0
	v_pk_mul_f32 v[190:191], v[156:157], v[160:161]
	v_pk_fma_f32 v[156:157], v[18:19], v[188:189], v[22:23]
	v_lshlrev_b32_e32 v160, 16, v159
	v_pk_fma_f32 v[156:157], v[2:3], v[174:175], v[156:157]
	v_and_b32_e32 v161, 0xffff0000, v159
	v_pk_fma_f32 v[156:157], v[6:7], v[168:169], v[156:157]
	s_nop 0
	v_pk_fma_f32 v[156:157], v[38:39], v[160:161], v[156:157]
	s_nop 0
	v_mul_f32_e32 v158, 0xbfb8aa3b, v156
	v_mul_f32_e32 v159, 0xbfb8aa3b, v157
	v_exp_f32_e32 v158, v158
	v_exp_f32_e32 v159, v159
	v_add_f32_e32 v158, 1.0, v158
	v_add_f32_e32 v159, 1.0, v159
	v_rcp_f32_e32 v158, v158
	v_rcp_f32_e32 v159, v159
	s_nop 0
	v_pk_mul_f32 v[188:189], v[156:157], v[158:159]
	v_cvt_pk_bf16_f32 v156, v176, v177
	v_or_b32_e32 v176, 5, v200
	v_ashrrev_i32_e32 v177, 31, v176
	v_lshlrev_b64 v[176:177], 12, v[176:177]
	v_cvt_pk_bf16_f32 v157, v182, v183
	v_cvt_pk_bf16_f32 v158, v190, v191
	v_cvt_pk_bf16_f32 v159, v188, v189
	v_lshl_add_u64 v[176:177], v[198:199], 0, v[176:177]
	global_store_dwordx4 v[176:177], v[156:159], off
	s_waitcnt vmcnt(22)
; DI float silu_(float x) { return x * __builtin_amdgcn_rcpf(1.f + __expf(-x)); }
; DI u32x4 pack8f(const float (&f)[8]) { u32x4 r; r[0] = pk2(f[0], f[1]); r[1] = pk2(f[2], f[3]); r[2] = pk2(f[4], f[5]); r[3] = pk2(f[6], f[7]); return r; }
; DI void conv0_phase(const bf16_t* X, const float* w, const float* bias, bf16_t* Y) {
;     ...
;         for (int r = 0; r < 19; ++r) cu[r] = nx[r];
;     ...
;         for (int r = 0; r < 16; ++r) {
;             float cur[8], y[8];
;             unpack8(cu[3 + r], cur);
; #pragma unroll
;             for (int e = 0; e < 8; ++e) { const float v = bb[e] + w0[e] * p3[e] + w1[e] * p2[e] + w2[e] * p1[e] + w3[e] * cur[e]; y[e] = silu_(v); p3[e] = p2[e]; p2[e] = p1[e]; p1[e] = cur[e]; }
;             *(u32x4*)(Y + (size_t)(t0 + r) * 2048 + c0) = pack8f(y);
;         }
	v_mov_b64_e32 v[190:191], v[50:51]
	v_mov_b64_e32 v[188:189], v[48:49]
	v_pk_fma_f32 v[156:157], v[24:25], v[186:187], v[28:29]
	v_lshlrev_b32_e32 v158, 16, v152
	v_pk_fma_f32 v[156:157], v[32:33], v[178:179], v[156:157]
	v_and_b32_e32 v159, 0xffff0000, v152
	v_pk_fma_f32 v[156:157], v[8:9], v[166:167], v[156:157]
	s_nop 0
	v_pk_fma_f32 v[156:157], v[12:13], v[158:159], v[156:157]
	s_nop 0
	v_mul_f32_e32 v152, 0xbfb8aa3b, v156
	v_exp_f32_e32 v152, v152
	s_nop 0
	v_add_f32_e32 v152, 1.0, v152
	v_rcp_f32_e32 v176, v152
	v_mul_f32_e32 v152, 0xbfb8aa3b, v157
	v_exp_f32_e32 v152, v152
	s_nop 0
	v_add_f32_e32 v152, 1.0, v152
	v_rcp_f32_e32 v177, v152
	s_nop 0
	v_pk_mul_f32 v[182:183], v[156:157], v[176:177]
	v_lshlrev_b32_e32 v156, 16, v153
	v_and_b32_e32 v157, 0xffff0000, v153
	v_pk_fma_f32 v[152:153], v[26:27], v[184:185], v[30:31]
	s_nop 0
	v_pk_fma_f32 v[152:153], v[34:35], v[172:173], v[152:153]
	v_pk_fma_f32 v[172:173], v[26:27], v[172:173], v[30:31]
	v_pk_fma_f32 v[152:153], v[10:11], v[164:165], v[152:153]
	v_pk_fma_f32 v[172:173], v[34:35], v[164:165], v[172:173]
	v_pk_fma_f32 v[152:153], v[14:15], v[156:157], v[152:153]
	v_pk_fma_f32 v[172:173], v[10:11], v[156:157], v[172:173]
	v_mul_f32_e32 v176, 0xbfb8aa3b, v152
	v_mul_f32_e32 v177, 0xbfb8aa3b, v153
	v_exp_f32_e32 v176, v176
	v_exp_f32_e32 v177, v177
	v_add_f32_e32 v176, 1.0, v176
	v_add_f32_e32 v177, 1.0, v177
	v_rcp_f32_e32 v176, v176
	v_rcp_f32_e32 v177, v177
	s_nop 0
	v_pk_mul_f32 v[184:185], v[152:153], v[176:177]
	v_pk_fma_f32 v[152:153], v[16:17], v[180:181], v[20:21]
	v_lshlrev_b32_e32 v176, 16, v154
	v_pk_fma_f32 v[152:153], v[0:1], v[170:171], v[152:153]
	v_and_b32_e32 v177, 0xffff0000, v154
	v_pk_fma_f32 v[152:153], v[4:5], v[162:163], v[152:153]
	v_pk_fma_f32 v[170:171], v[16:17], v[170:171], v[20:21]
	v_pk_fma_f32 v[152:153], v[36:37], v[176:177], v[152:153]
	v_pk_fma_f32 v[170:171], v[0:1], v[162:163], v[170:171]
	v_mul_f32_e32 v154, 0xbfb8aa3b, v152
	v_exp_f32_e32 v154, v154
	v_pk_fma_f32 v[170:171], v[4:5], v[176:177], v[170:171]
	v_add_f32_e32 v154, 1.0, v154
	v_rcp_f32_e32 v180, v154
	v_mul_f32_e32 v154, 0xbfb8aa3b, v153
	v_exp_f32_e32 v154, v154
	s_nop 0
	v_add_f32_e32 v154, 1.0, v154
	v_rcp_f32_e32 v181, v154
	s_nop 0
	v_pk_mul_f32 v[186:187], v[152:153], v[180:181]
	v_lshlrev_b32_e32 v152, 16, v155
	v_and_b32_e32 v153, 0xffff0000, v155
	v_pk_fma_f32 v[154:155], v[18:19], v[174:175], v[22:23]
	v_cvt_pk_bf16_f32 v180, v182, v183
	v_pk_fma_f32 v[154:155], v[2:3], v[168:169], v[154:155]
	v_cvt_pk_bf16_f32 v181, v184, v185
	v_pk_fma_f32 v[154:155], v[6:7], v[160:161], v[154:155]
	v_cvt_pk_bf16_f32 v182, v186, v187
	v_pk_fma_f32 v[154:155], v[38:39], v[152:153], v[154:155]
	v_mov_b64_e32 v[186:187], v[42:43]
	v_mul_f32_e32 v174, 0xbfb8aa3b, v154
	v_mul_f32_e32 v175, 0xbfb8aa3b, v155
	v_exp_f32_e32 v174, v174
	v_exp_f32_e32 v175, v175
	v_mov_b64_e32 v[184:185], v[40:41]
	v_add_f32_e32 v174, 1.0, v174
	v_add_f32_e32 v175, 1.0, v175
	v_rcp_f32_e32 v174, v174
	v_rcp_f32_e32 v175, v175
	s_nop 0
	v_pk_mul_f32 v[154:155], v[154:155], v[174:175]
	s_nop 0
	v_cvt_pk_bf16_f32 v183, v154, v155
	v_or_b32_e32 v154, 6, v200
	v_ashrrev_i32_e32 v155, 31, v154
	v_lshlrev_b64 v[154:155], 12, v[154:155]
	v_lshl_add_u64 v[154:155], v[198:199], 0, v[154:155]
	global_store_dwordx4 v[154:155], v[180:183], off
	v_pk_fma_f32 v[154:155], v[24:25], v[178:179], v[28:29]
	v_lshlrev_b32_e32 v174, 16, v148
	v_pk_fma_f32 v[154:155], v[32:33], v[166:167], v[154:155]
	v_and_b32_e32 v175, 0xffff0000, v148
	v_pk_fma_f32 v[154:155], v[8:9], v[158:159], v[154:155]
	s_nop 0
	v_pk_fma_f32 v[154:155], v[12:13], v[174:175], v[154:155]
	s_nop 0
	v_mul_f32_e32 v148, 0xbfb8aa3b, v154
	v_exp_f32_e32 v148, v148
	s_nop 0
	v_add_f32_e32 v148, 1.0, v148
	v_rcp_f32_e32 v178, v148
	v_mul_f32_e32 v148, 0xbfb8aa3b, v155
	v_exp_f32_e32 v148, v148
	s_nop 0
	v_add_f32_e32 v148, 1.0, v148
	v_rcp_f32_e32 v179, v148
	v_lshlrev_b32_e32 v148, 16, v149
	v_and_b32_e32 v149, 0xffff0000, v149
	v_pk_fma_f32 v[172:173], v[14:15], v[148:149], v[172:173]
	v_pk_mul_f32 v[154:155], v[154:155], v[178:179]
	v_mul_f32_e32 v178, 0xbfb8aa3b, v172
	v_mul_f32_e32 v179, 0xbfb8aa3b, v173
	v_exp_f32_e32 v178, v178
	v_exp_f32_e32 v179, v179
	v_add_f32_e32 v178, 1.0, v178
	v_add_f32_e32 v179, 1.0, v179
	v_rcp_f32_e32 v178, v178
	v_rcp_f32_e32 v179, v179
	s_nop 0
	v_pk_mul_f32 v[180:181], v[172:173], v[178:179]
	v_lshlrev_b32_e32 v172, 16, v150
	v_and_b32_e32 v173, 0xffff0000, v150
	v_pk_fma_f32 v[170:171], v[36:37], v[172:173], v[170:171]
	s_nop 0
	v_mul_f32_e32 v150, 0xbfb8aa3b, v170
	v_exp_f32_e32 v150, v150
	s_nop 0
	v_add_f32_e32 v150, 1.0, v150
	v_rcp_f32_e32 v178, v150
	v_mul_f32_e32 v150, 0xbfb8aa3b, v171
	v_exp_f32_e32 v150, v150
	s_nop 0
	v_add_f32_e32 v150, 1.0, v150
	v_rcp_f32_e32 v179, v150
	s_nop 0
	v_pk_mul_f32 v[182:183], v[170:171], v[178:179]
	v_lshlrev_b32_e32 v170, 16, v151
	v_and_b32_e32 v171, 0xffff0000, v151
	v_pk_fma_f32 v[150:151], v[18:19], v[168:169], v[22:23]
	v_cvt_pk_bf16_f32 v179, v180, v181
	v_pk_fma_f32 v[150:151], v[2:3], v[160:161], v[150:151]
	v_cvt_pk_bf16_f32 v178, v154, v155
	v_pk_fma_f32 v[150:151], v[6:7], v[152:153], v[150:151]
	v_cvt_pk_bf16_f32 v180, v182, v183
	v_pk_fma_f32 v[150:151], v[38:39], v[170:171], v[150:151]
	s_nop 0
	v_mul_f32_e32 v168, 0xbfb8aa3b, v150
	v_mul_f32_e32 v169, 0xbfb8aa3b, v151
	v_exp_f32_e32 v168, v168
	v_exp_f32_e32 v169, v169
	v_add_f32_e32 v168, 1.0, v168
	v_add_f32_e32 v169, 1.0, v169
	v_rcp_f32_e32 v168, v168
	v_rcp_f32_e32 v169, v169
	s_nop 0
	v_pk_mul_f32 v[150:151], v[150:151], v[168:169]
	s_nop 0
	v_cvt_pk_bf16_f32 v181, v150, v151
	v_or_b32_e32 v150, 7, v200
; DI float silu_(float x) { return x * __builtin_amdgcn_rcpf(1.f + __expf(-x)); }
; DI u32x4 pack8f(const float (&f)[8]) { u32x4 r; r[0] = pk2(f[0], f[1]); r[1] = pk2(f[2], f[3]); r[2] = pk2(f[4], f[5]); r[3] = pk2(f[6], f[7]); return r; }
; DI void conv0_phase(const bf16_t* X, const float* w, const float* bias, bf16_t* Y) {
;     ...
;         for (int r = 0; r < 19; ++r) cu[r] = nx[r];
;         if (it + stride < total) {
;             const int t1 = ((it + stride) >> 8) * 16; const bool f1 = (t1 & 2047) == 0;
; #pragma unroll
;             for (int r = 0; r < 19; ++r) { const int t = (f1 && r < 3) ? t1 : t1 - 3 + r; nx[r] = *(const u32x4*)(X + (size_t)t * 2048 + c0); }
;     ...
;         for (int r = 0; r < 16; ++r) {
;             float cur[8], y[8];
;             unpack8(cu[3 + r], cur);
; #pragma unroll
;             for (int e = 0; e < 8; ++e) { const float v = bb[e] + w0[e] * p3[e] + w1[e] * p2[e] + w2[e] * p1[e] + w3[e] * cur[e]; y[e] = silu_(v); p3[e] = p2[e]; p2[e] = p1[e]; p1[e] = cur[e]; }
;             *(u32x4*)(Y + (size_t)(t0 + r) * 2048 + c0) = pack8f(y);
;         }
	v_ashrrev_i32_e32 v151, 31, v150
	v_lshlrev_b64 v[150:151], 12, v[150:151]
	v_lshl_add_u64 v[150:151], v[198:199], 0, v[150:151]
	global_store_dwordx4 v[150:151], v[178:181], off
	v_pk_fma_f32 v[150:151], v[24:25], v[166:167], v[28:29]
	v_lshlrev_b32_e32 v168, 16, v144
	v_pk_fma_f32 v[150:151], v[32:33], v[158:159], v[150:151]
	v_and_b32_e32 v169, 0xffff0000, v144
	v_pk_fma_f32 v[150:151], v[8:9], v[174:175], v[150:151]
	v_lshlrev_b32_e32 v166, 16, v145
	v_pk_fma_f32 v[150:151], v[12:13], v[168:169], v[150:151]
	v_and_b32_e32 v167, 0xffff0000, v145
	v_mul_f32_e32 v144, 0xbfb8aa3b, v150
	v_exp_f32_e32 v144, v144
	v_mov_b64_e32 v[182:183], v[46:47]
	v_mov_b64_e32 v[180:181], v[44:45]
	v_add_f32_e32 v144, 1.0, v144
	v_rcp_f32_e32 v154, v144
	v_mul_f32_e32 v144, 0xbfb8aa3b, v151
	v_exp_f32_e32 v144, v144
	s_nop 0
	v_add_f32_e32 v144, 1.0, v144
	v_rcp_f32_e32 v155, v144
	v_pk_fma_f32 v[144:145], v[26:27], v[164:165], v[30:31]
	v_lshlrev_b32_e32 v164, 16, v146
	v_pk_fma_f32 v[144:145], v[34:35], v[156:157], v[144:145]
	v_pk_mul_f32 v[150:151], v[150:151], v[154:155]
	v_pk_fma_f32 v[144:145], v[10:11], v[148:149], v[144:145]
	v_and_b32_e32 v165, 0xffff0000, v146
	v_pk_fma_f32 v[144:145], v[14:15], v[166:167], v[144:145]
	s_nop 0
	v_mul_f32_e32 v154, 0xbfb8aa3b, v144
	v_mul_f32_e32 v155, 0xbfb8aa3b, v145
	v_exp_f32_e32 v154, v154
	v_exp_f32_e32 v155, v155
	v_add_f32_e32 v154, 1.0, v154
	v_add_f32_e32 v155, 1.0, v155
	v_rcp_f32_e32 v154, v154
	v_rcp_f32_e32 v155, v155
	s_nop 0
	v_pk_mul_f32 v[154:155], v[144:145], v[154:155]
	v_pk_fma_f32 v[144:145], v[16:17], v[162:163], v[20:21]
	s_nop 0
	v_pk_fma_f32 v[144:145], v[0:1], v[176:177], v[144:145]
	s_nop 0
	v_pk_fma_f32 v[144:145], v[4:5], v[172:173], v[144:145]
	s_nop 0
	v_pk_fma_f32 v[144:145], v[36:37], v[164:165], v[144:145]
	s_nop 0
	v_mul_f32_e32 v146, 0xbfb8aa3b, v144
	v_exp_f32_e32 v146, v146
	s_nop 0
	v_add_f32_e32 v146, 1.0, v146
	v_rcp_f32_e32 v162, v146
	v_mul_f32_e32 v146, 0xbfb8aa3b, v145
	v_exp_f32_e32 v146, v146
	s_nop 0
	v_add_f32_e32 v146, 1.0, v146
	v_rcp_f32_e32 v163, v146
	s_nop 0
	v_pk_mul_f32 v[178:179], v[144:145], v[162:163]
	v_pk_fma_f32 v[144:145], v[18:19], v[160:161], v[22:23]
	v_lshlrev_b32_e32 v162, 16, v147
	v_pk_fma_f32 v[144:145], v[2:3], v[152:153], v[144:145]
	v_and_b32_e32 v163, 0xffff0000, v147
	v_pk_fma_f32 v[144:145], v[6:7], v[170:171], v[144:145]
	s_nop 0
	v_pk_fma_f32 v[144:145], v[38:39], v[162:163], v[144:145]
	s_nop 0
	v_mul_f32_e32 v146, 0xbfb8aa3b, v144
	v_mul_f32_e32 v147, 0xbfb8aa3b, v145
	v_exp_f32_e32 v146, v146
	v_exp_f32_e32 v147, v147
	v_add_f32_e32 v146, 1.0, v146
	v_add_f32_e32 v147, 1.0, v147
	v_rcp_f32_e32 v146, v146
	v_rcp_f32_e32 v147, v147
	s_nop 0
	v_pk_mul_f32 v[160:161], v[144:145], v[146:147]
	v_cvt_pk_bf16_f32 v144, v150, v151
	v_or_b32_e32 v150, 8, v200
	v_ashrrev_i32_e32 v151, 31, v150
	v_lshlrev_b64 v[150:151], 12, v[150:151]
	v_cvt_pk_bf16_f32 v145, v154, v155
	v_cvt_pk_bf16_f32 v146, v178, v179
	v_cvt_pk_bf16_f32 v147, v160, v161
	v_lshl_add_u64 v[150:151], v[198:199], 0, v[150:151]
	global_store_dwordx4 v[150:151], v[144:147], off
	v_lshlrev_b32_e32 v160, 16, v140
	v_and_b32_e32 v161, 0xffff0000, v140
	v_pk_fma_f32 v[144:145], v[24:25], v[158:159], v[28:29]
	v_lshlrev_b32_e32 v158, 16, v141
	v_pk_fma_f32 v[144:145], v[32:33], v[174:175], v[144:145]
	v_and_b32_e32 v159, 0xffff0000, v141
	v_pk_fma_f32 v[144:145], v[8:9], v[168:169], v[144:145]
	v_lshlrev_b32_e32 v154, 16, v143
	v_pk_fma_f32 v[144:145], v[12:13], v[160:161], v[144:145]
	v_and_b32_e32 v155, 0xffff0000, v143
	v_mul_f32_e32 v140, 0xbfb8aa3b, v144
	v_exp_f32_e32 v140, v140
	s_nop 0
	v_add_f32_e32 v140, 1.0, v140
	v_rcp_f32_e32 v146, v140
	v_mul_f32_e32 v140, 0xbfb8aa3b, v145
	v_exp_f32_e32 v140, v140
	s_nop 0
	v_add_f32_e32 v140, 1.0, v140
	v_rcp_f32_e32 v147, v140
	v_pk_fma_f32 v[140:141], v[26:27], v[156:157], v[30:31]
	v_lshlrev_b32_e32 v156, 16, v142
	v_pk_fma_f32 v[140:141], v[34:35], v[148:149], v[140:141]
	v_pk_mul_f32 v[144:145], v[144:145], v[146:147]
	v_pk_fma_f32 v[140:141], v[10:11], v[166:167], v[140:141]
	v_and_b32_e32 v157, 0xffff0000, v142
	v_pk_fma_f32 v[140:141], v[14:15], v[158:159], v[140:141]
	s_nop 0
	v_mul_f32_e32 v146, 0xbfb8aa3b, v140
	v_mul_f32_e32 v147, 0xbfb8aa3b, v141
	v_exp_f32_e32 v146, v146
	v_exp_f32_e32 v147, v147
	v_add_f32_e32 v146, 1.0, v146
	v_add_f32_e32 v147, 1.0, v147
	v_rcp_f32_e32 v146, v146
	v_rcp_f32_e32 v147, v147
	s_nop 0
	v_pk_mul_f32 v[146:147], v[140:141], v[146:147]
	v_pk_fma_f32 v[140:141], v[16:17], v[176:177], v[20:21]
	s_waitcnt vmcnt(24)
; DI float silu_(float x) { return x * __builtin_amdgcn_rcpf(1.f + __expf(-x)); }
; DI u32x4 pack8f(const float (&f)[8]) { u32x4 r; r[0] = pk2(f[0], f[1]); r[1] = pk2(f[2], f[3]); r[2] = pk2(f[4], f[5]); r[3] = pk2(f[6], f[7]); return r; }
; DI void conv0_phase(const bf16_t* X, const float* w, const float* bias, bf16_t* Y) {
;     ...
;         for (int r = 0; r < 19; ++r) cu[r] = nx[r];
;         if (it + stride < total) {
;             const int t1 = ((it + stride) >> 8) * 16; const bool f1 = (t1 & 2047) == 0;
; #pragma unroll
;             for (int r = 0; r < 19; ++r) { const int t = (f1 && r < 3) ? t1 : t1 - 3 + r; nx[r] = *(const u32x4*)(X + (size_t)t * 2048 + c0); }
;     ...
;         for (int r = 0; r < 16; ++r) {
;             float cur[8], y[8];
;             unpack8(cu[3 + r], cur);
; #pragma unroll
;             for (int e = 0; e < 8; ++e) { const float v = bb[e] + w0[e] * p3[e] + w1[e] * p2[e] + w2[e] * p1[e] + w3[e] * cur[e]; y[e] = silu_(v); p3[e] = p2[e]; p2[e] = p1[e]; p1[e] = cur[e]; }
;             *(u32x4*)(Y + (size_t)(t0 + r) * 2048 + c0) = pack8f(y);
;         }
	v_mov_b64_e32 v[178:179], v[54:55]
	v_pk_fma_f32 v[140:141], v[0:1], v[172:173], v[140:141]
	v_mov_b64_e32 v[176:177], v[52:53]
	v_pk_fma_f32 v[140:141], v[4:5], v[164:165], v[140:141]
	s_nop 0
	v_pk_fma_f32 v[140:141], v[36:37], v[156:157], v[140:141]
	s_nop 0
	v_mul_f32_e32 v142, 0xbfb8aa3b, v140
	v_exp_f32_e32 v142, v142
	s_nop 0
	v_add_f32_e32 v142, 1.0, v142
	v_rcp_f32_e32 v150, v142
	v_mul_f32_e32 v142, 0xbfb8aa3b, v141
	v_exp_f32_e32 v142, v142
	s_nop 0
	v_add_f32_e32 v142, 1.0, v142
	v_rcp_f32_e32 v151, v142
	s_nop 0
	v_pk_mul_f32 v[150:151], v[140:141], v[150:151]
	v_pk_fma_f32 v[140:141], v[18:19], v[152:153], v[22:23]
	s_nop 0
	v_pk_fma_f32 v[140:141], v[2:3], v[170:171], v[140:141]
	s_nop 0
	v_pk_fma_f32 v[140:141], v[6:7], v[162:163], v[140:141]
	s_nop 0
	v_pk_fma_f32 v[140:141], v[38:39], v[154:155], v[140:141]
	s_nop 0
	v_mul_f32_e32 v142, 0xbfb8aa3b, v140
	v_mul_f32_e32 v143, 0xbfb8aa3b, v141
	v_exp_f32_e32 v142, v142
	v_exp_f32_e32 v143, v143
	v_add_f32_e32 v142, 1.0, v142
	v_add_f32_e32 v143, 1.0, v143
	v_rcp_f32_e32 v142, v142
	v_rcp_f32_e32 v143, v143
	s_nop 0
	v_pk_mul_f32 v[152:153], v[140:141], v[142:143]
	v_cvt_pk_bf16_f32 v140, v144, v145
	v_or_b32_e32 v144, 9, v200
	v_ashrrev_i32_e32 v145, 31, v144
	v_lshlrev_b64 v[144:145], 12, v[144:145]
	v_cvt_pk_bf16_f32 v141, v146, v147
	v_cvt_pk_bf16_f32 v142, v150, v151
	v_cvt_pk_bf16_f32 v143, v152, v153
	v_lshl_add_u64 v[144:145], v[198:199], 0, v[144:145]
	global_store_dwordx4 v[144:145], v[140:143], off
	v_lshlrev_b32_e32 v152, 16, v136
	v_and_b32_e32 v153, 0xffff0000, v136
	v_pk_fma_f32 v[140:141], v[24:25], v[174:175], v[28:29]
	v_lshlrev_b32_e32 v150, 16, v137
	v_pk_fma_f32 v[140:141], v[32:33], v[168:169], v[140:141]
	v_and_b32_e32 v151, 0xffff0000, v137
	v_pk_fma_f32 v[140:141], v[8:9], v[160:161], v[140:141]
	v_lshlrev_b32_e32 v146, 16, v139
	v_pk_fma_f32 v[140:141], v[12:13], v[152:153], v[140:141]
	v_and_b32_e32 v147, 0xffff0000, v139
	v_mul_f32_e32 v136, 0xbfb8aa3b, v140
	v_exp_f32_e32 v136, v136
	s_nop 0
	v_add_f32_e32 v136, 1.0, v136
	v_rcp_f32_e32 v142, v136
	v_mul_f32_e32 v136, 0xbfb8aa3b, v141
	v_exp_f32_e32 v136, v136
	s_nop 0
	v_add_f32_e32 v136, 1.0, v136
	v_rcp_f32_e32 v143, v136
	v_pk_fma_f32 v[136:137], v[26:27], v[148:149], v[30:31]
	v_lshlrev_b32_e32 v148, 16, v138
	v_pk_fma_f32 v[136:137], v[34:35], v[166:167], v[136:137]
	v_pk_mul_f32 v[140:141], v[140:141], v[142:143]
	v_pk_fma_f32 v[136:137], v[10:11], v[158:159], v[136:137]
	v_and_b32_e32 v149, 0xffff0000, v138
	v_pk_fma_f32 v[136:137], v[14:15], v[150:151], v[136:137]
	s_nop 0
	v_mul_f32_e32 v142, 0xbfb8aa3b, v136
	v_mul_f32_e32 v143, 0xbfb8aa3b, v137
	v_exp_f32_e32 v142, v142
	v_exp_f32_e32 v143, v143
	v_add_f32_e32 v142, 1.0, v142
	v_add_f32_e32 v143, 1.0, v143
	v_rcp_f32_e32 v142, v142
	v_rcp_f32_e32 v143, v143
	s_nop 0
	v_pk_mul_f32 v[142:143], v[136:137], v[142:143]
	v_pk_fma_f32 v[136:137], v[16:17], v[172:173], v[20:21]
	s_waitcnt vmcnt(24)
	v_mov_b64_e32 v[174:175], v[58:59]
	v_pk_fma_f32 v[136:137], v[0:1], v[164:165], v[136:137]
	v_mov_b64_e32 v[172:173], v[56:57]
	v_pk_fma_f32 v[136:137], v[4:5], v[156:157], v[136:137]
	s_nop 0
	v_pk_fma_f32 v[136:137], v[36:37], v[148:149], v[136:137]
	s_nop 0
	v_mul_f32_e32 v138, 0xbfb8aa3b, v136
	v_exp_f32_e32 v138, v138
	s_nop 0
	v_add_f32_e32 v138, 1.0, v138
	v_rcp_f32_e32 v144, v138
	v_mul_f32_e32 v138, 0xbfb8aa3b, v137
	v_exp_f32_e32 v138, v138
	s_nop 0
	v_add_f32_e32 v138, 1.0, v138
	v_rcp_f32_e32 v145, v138
	s_nop 0
	v_pk_mul_f32 v[144:145], v[136:137], v[144:145]
	v_pk_fma_f32 v[136:137], v[18:19], v[170:171], v[22:23]
	s_nop 0
	v_pk_fma_f32 v[136:137], v[2:3], v[162:163], v[136:137]
	s_nop 0
	v_pk_fma_f32 v[136:137], v[6:7], v[154:155], v[136:137]
	s_nop 0
	v_pk_fma_f32 v[136:137], v[38:39], v[146:147], v[136:137]
	s_nop 0
	v_mul_f32_e32 v138, 0xbfb8aa3b, v136
	v_mul_f32_e32 v139, 0xbfb8aa3b, v137
	v_exp_f32_e32 v138, v138
	v_exp_f32_e32 v139, v139
	v_add_f32_e32 v138, 1.0, v138
	v_add_f32_e32 v139, 1.0, v139
	v_rcp_f32_e32 v138, v138
	v_rcp_f32_e32 v139, v139
	s_nop 0
	v_pk_mul_f32 v[170:171], v[136:137], v[138:139]
	v_cvt_pk_bf16_f32 v136, v140, v141
	v_or_b32_e32 v140, 10, v200
	v_ashrrev_i32_e32 v141, 31, v140
	v_lshlrev_b64 v[140:141], 12, v[140:141]
	v_cvt_pk_bf16_f32 v137, v142, v143
	v_cvt_pk_bf16_f32 v138, v144, v145
	v_cvt_pk_bf16_f32 v139, v170, v171
	v_lshl_add_u64 v[140:141], v[198:199], 0, v[140:141]
	global_store_dwordx4 v[140:141], v[136:139], off
	v_lshlrev_b32_e32 v144, 16, v132
	v_and_b32_e32 v145, 0xffff0000, v132
	v_pk_fma_f32 v[136:137], v[24:25], v[168:169], v[28:29]
	v_lshlrev_b32_e32 v142, 16, v133
	v_pk_fma_f32 v[136:137], v[32:33], v[160:161], v[136:137]
	v_and_b32_e32 v143, 0xffff0000, v133
	v_pk_fma_f32 v[136:137], v[8:9], v[152:153], v[136:137]
	v_lshlrev_b32_e32 v140, 16, v134
	v_pk_fma_f32 v[136:137], v[12:13], v[144:145], v[136:137]
	v_and_b32_e32 v141, 0xffff0000, v134
	v_mul_f32_e32 v132, 0xbfb8aa3b, v136
	v_exp_f32_e32 v132, v132
	s_waitcnt vmcnt(24)
; DI float silu_(float x) { return x * __builtin_amdgcn_rcpf(1.f + __expf(-x)); }
; DI u32x4 pack8f(const float (&f)[8]) { u32x4 r; r[0] = pk2(f[0], f[1]); r[1] = pk2(f[2], f[3]); r[2] = pk2(f[4], f[5]); r[3] = pk2(f[6], f[7]); return r; }
; DI void conv0_phase(const bf16_t* X, const float* w, const float* bias, bf16_t* Y) {
;     ...
;         for (int r = 0; r < 19; ++r) cu[r] = nx[r];
;         if (it + stride < total) {
;             const int t1 = ((it + stride) >> 8) * 16; const bool f1 = (t1 & 2047) == 0;
; #pragma unroll
;             for (int r = 0; r < 19; ++r) { const int t = (f1 && r < 3) ? t1 : t1 - 3 + r; nx[r] = *(const u32x4*)(X + (size_t)t * 2048 + c0); }
;     ...
;         for (int r = 0; r < 16; ++r) {
;             float cur[8], y[8];
;             unpack8(cu[3 + r], cur);
; #pragma unroll
;             for (int e = 0; e < 8; ++e) { const float v = bb[e] + w0[e] * p3[e] + w1[e] * p2[e] + w2[e] * p1[e] + w3[e] * cur[e]; y[e] = silu_(v); p3[e] = p2[e]; p2[e] = p1[e]; p1[e] = cur[e]; }
;             *(u32x4*)(Y + (size_t)(t0 + r) * 2048 + c0) = pack8f(y);
;         }
	v_mov_b64_e32 v[170:171], v[62:63]
	v_mov_b64_e32 v[168:169], v[60:61]
	v_add_f32_e32 v132, 1.0, v132
	v_rcp_f32_e32 v138, v132
	v_mul_f32_e32 v132, 0xbfb8aa3b, v137
	v_exp_f32_e32 v132, v132
	s_nop 0
	v_add_f32_e32 v132, 1.0, v132
	v_rcp_f32_e32 v139, v132
	v_pk_fma_f32 v[132:133], v[26:27], v[166:167], v[30:31]
	v_pk_mul_f32 v[136:137], v[136:137], v[138:139]
	v_pk_fma_f32 v[132:133], v[34:35], v[158:159], v[132:133]
	s_nop 0
	v_pk_fma_f32 v[132:133], v[10:11], v[150:151], v[132:133]
	s_nop 0
	v_pk_fma_f32 v[132:133], v[14:15], v[142:143], v[132:133]
	s_nop 0
	v_mul_f32_e32 v138, 0xbfb8aa3b, v132
	v_mul_f32_e32 v139, 0xbfb8aa3b, v133
	v_exp_f32_e32 v138, v138
	v_exp_f32_e32 v139, v139
	v_add_f32_e32 v138, 1.0, v138
	v_add_f32_e32 v139, 1.0, v139
	v_rcp_f32_e32 v138, v138
	v_rcp_f32_e32 v139, v139
	s_nop 0
	v_pk_mul_f32 v[166:167], v[132:133], v[138:139]
	v_pk_fma_f32 v[132:133], v[16:17], v[164:165], v[20:21]
	s_nop 0
	v_pk_fma_f32 v[132:133], v[0:1], v[156:157], v[132:133]
	s_nop 0
	v_pk_fma_f32 v[132:133], v[4:5], v[148:149], v[132:133]
	s_nop 0
	v_pk_fma_f32 v[132:133], v[36:37], v[140:141], v[132:133]
	s_nop 0
	v_mul_f32_e32 v134, 0xbfb8aa3b, v132
	v_exp_f32_e32 v134, v134
	s_nop 0
	v_add_f32_e32 v134, 1.0, v134
	v_rcp_f32_e32 v138, v134
	v_mul_f32_e32 v134, 0xbfb8aa3b, v133
	v_exp_f32_e32 v134, v134
	s_nop 0
	v_add_f32_e32 v134, 1.0, v134
	v_rcp_f32_e32 v139, v134
	s_nop 0
	v_pk_mul_f32 v[164:165], v[132:133], v[138:139]
	v_pk_fma_f32 v[132:133], v[18:19], v[162:163], v[22:23]
	v_lshlrev_b32_e32 v138, 16, v135
	v_pk_fma_f32 v[132:133], v[2:3], v[154:155], v[132:133]
	v_and_b32_e32 v139, 0xffff0000, v135
	v_pk_fma_f32 v[132:133], v[6:7], v[146:147], v[132:133]
	s_nop 0
	v_pk_fma_f32 v[132:133], v[38:39], v[138:139], v[132:133]
	s_nop 0
	v_mul_f32_e32 v134, 0xbfb8aa3b, v132
	v_mul_f32_e32 v135, 0xbfb8aa3b, v133
	v_exp_f32_e32 v134, v134
	v_exp_f32_e32 v135, v135
	v_add_f32_e32 v134, 1.0, v134
	v_add_f32_e32 v135, 1.0, v135
	v_rcp_f32_e32 v134, v134
	v_rcp_f32_e32 v135, v135
	s_nop 0
	v_pk_mul_f32 v[162:163], v[132:133], v[134:135]
	v_cvt_pk_bf16_f32 v132, v136, v137
	v_or_b32_e32 v136, 11, v200
	v_ashrrev_i32_e32 v137, 31, v136
	v_lshlrev_b64 v[136:137], 12, v[136:137]
	v_cvt_pk_bf16_f32 v133, v166, v167
	v_cvt_pk_bf16_f32 v134, v164, v165
	v_cvt_pk_bf16_f32 v135, v162, v163
	v_lshl_add_u64 v[136:137], v[198:199], 0, v[136:137]
	global_store_dwordx4 v[136:137], v[132:135], off
	v_lshlrev_b32_e32 v136, 16, v128
	v_and_b32_e32 v137, 0xffff0000, v128
	v_pk_fma_f32 v[132:133], v[24:25], v[160:161], v[28:29]
	s_waitcnt vmcnt(24)
	v_mov_b64_e32 v[166:167], v[66:67]
	v_pk_fma_f32 v[132:133], v[32:33], v[152:153], v[132:133]
	v_mov_b64_e32 v[164:165], v[64:65]
	v_pk_fma_f32 v[132:133], v[8:9], v[144:145], v[132:133]
	s_nop 0
	v_pk_fma_f32 v[132:133], v[12:13], v[136:137], v[132:133]
	s_nop 0
	v_mul_f32_e32 v128, 0xbfb8aa3b, v132
	v_exp_f32_e32 v128, v128
	s_nop 0
	v_add_f32_e32 v128, 1.0, v128
	v_rcp_f32_e32 v134, v128
	v_mul_f32_e32 v128, 0xbfb8aa3b, v133
	v_exp_f32_e32 v128, v128
	s_nop 0
	v_add_f32_e32 v128, 1.0, v128
	v_rcp_f32_e32 v135, v128
	s_nop 0
	v_pk_mul_f32 v[160:161], v[132:133], v[134:135]
	v_lshlrev_b32_e32 v134, 16, v129
	v_and_b32_e32 v135, 0xffff0000, v129
	v_pk_fma_f32 v[128:129], v[26:27], v[158:159], v[30:31]
	s_nop 0
	v_pk_fma_f32 v[128:129], v[34:35], v[150:151], v[128:129]
	s_nop 0
	v_pk_fma_f32 v[128:129], v[10:11], v[142:143], v[128:129]
	s_nop 0
	v_pk_fma_f32 v[128:129], v[14:15], v[134:135], v[128:129]
	s_nop 0
	v_mul_f32_e32 v132, 0xbfb8aa3b, v128
	v_mul_f32_e32 v133, 0xbfb8aa3b, v129
	v_exp_f32_e32 v132, v132
	v_exp_f32_e32 v133, v133
	v_add_f32_e32 v132, 1.0, v132
	v_add_f32_e32 v133, 1.0, v133
	v_rcp_f32_e32 v132, v132
	v_rcp_f32_e32 v133, v133
	s_nop 0
	v_pk_mul_f32 v[158:159], v[128:129], v[132:133]
	v_pk_fma_f32 v[128:129], v[16:17], v[156:157], v[20:21]
	v_lshlrev_b32_e32 v132, 16, v130
	v_pk_fma_f32 v[128:129], v[0:1], v[148:149], v[128:129]
	v_and_b32_e32 v133, 0xffff0000, v130
	v_pk_fma_f32 v[128:129], v[4:5], v[140:141], v[128:129]
	s_nop 0
	v_pk_fma_f32 v[128:129], v[36:37], v[132:133], v[128:129]
	s_nop 0
	v_mul_f32_e32 v130, 0xbfb8aa3b, v128
	v_exp_f32_e32 v130, v130
	s_nop 0
	v_add_f32_e32 v130, 1.0, v130
	v_rcp_f32_e32 v156, v130
	v_mul_f32_e32 v130, 0xbfb8aa3b, v129
	v_exp_f32_e32 v130, v130
	s_nop 0
	v_add_f32_e32 v130, 1.0, v130
	v_rcp_f32_e32 v157, v130
	s_nop 0
	v_pk_mul_f32 v[156:157], v[128:129], v[156:157]
	v_lshlrev_b32_e32 v128, 16, v131
	v_and_b32_e32 v129, 0xffff0000, v131
	v_pk_fma_f32 v[130:131], v[18:19], v[154:155], v[22:23]
	v_cvt_pk_bf16_f32 v156, v156, v157
	v_pk_fma_f32 v[130:131], v[2:3], v[146:147], v[130:131]
	s_nop 0
	v_pk_fma_f32 v[130:131], v[6:7], v[138:139], v[130:131]
	s_nop 0
	v_pk_fma_f32 v[130:131], v[38:39], v[128:129], v[130:131]
	s_nop 0
	v_mul_f32_e32 v154, 0xbfb8aa3b, v130
	v_mul_f32_e32 v155, 0xbfb8aa3b, v131
	v_exp_f32_e32 v154, v154
	v_exp_f32_e32 v155, v155
	v_add_f32_e32 v154, 1.0, v154
	v_add_f32_e32 v155, 1.0, v155
	v_rcp_f32_e32 v154, v154
	v_rcp_f32_e32 v155, v155
	s_nop 0
	v_pk_mul_f32 v[130:131], v[130:131], v[154:155]
	s_nop 0
	v_cvt_pk_bf16_f32 v157, v130, v131
	v_or_b32_e32 v130, 12, v200
	v_ashrrev_i32_e32 v131, 31, v130
	v_lshlrev_b64 v[130:131], 12, v[130:131]
	v_cvt_pk_bf16_f32 v154, v160, v161
	v_cvt_pk_bf16_f32 v155, v158, v159
	v_lshl_add_u64 v[130:131], v[198:199], 0, v[130:131]
	global_store_dwordx4 v[130:131], v[154:157], off
	v_pk_fma_f32 v[130:131], v[24:25], v[152:153], v[28:29]
	s_waitcnt vmcnt(24)
; DI float silu_(float x) { return x * __builtin_amdgcn_rcpf(1.f + __expf(-x)); }
; DI u32x4 pack8f(const float (&f)[8]) { u32x4 r; r[0] = pk2(f[0], f[1]); r[1] = pk2(f[2], f[3]); r[2] = pk2(f[4], f[5]); r[3] = pk2(f[6], f[7]); return r; }
; DI void conv0_phase(const bf16_t* X, const float* w, const float* bias, bf16_t* Y) {
;     ...
;         for (int r = 0; r < 19; ++r) cu[r] = nx[r];
;         if (it + stride < total) {
;             const int t1 = ((it + stride) >> 8) * 16; const bool f1 = (t1 & 2047) == 0;
; #pragma unroll
;             for (int r = 0; r < 19; ++r) { const int t = (f1 && r < 3) ? t1 : t1 - 3 + r; nx[r] = *(const u32x4*)(X + (size_t)t * 2048 + c0); }
;     ...
;         for (int r = 0; r < 16; ++r) {
;             float cur[8], y[8];
;             unpack8(cu[3 + r], cur);
; #pragma unroll
;             for (int e = 0; e < 8; ++e) { const float v = bb[e] + w0[e] * p3[e] + w1[e] * p2[e] + w2[e] * p1[e] + w3[e] * cur[e]; y[e] = silu_(v); p3[e] = p2[e]; p2[e] = p1[e]; p1[e] = cur[e]; }
;             *(u32x4*)(Y + (size_t)(t0 + r) * 2048 + c0) = pack8f(y);
;         }
	v_mov_b64_e32 v[162:163], v[70:71]
	v_pk_fma_f32 v[130:131], v[32:33], v[144:145], v[130:131]
	v_lshlrev_b32_e32 v154, 16, v124
	v_and_b32_e32 v155, 0xffff0000, v124
	v_pk_fma_f32 v[130:131], v[8:9], v[136:137], v[130:131]
	v_pk_fma_f32 v[144:145], v[24:25], v[144:145], v[28:29]
	v_pk_fma_f32 v[130:131], v[12:13], v[154:155], v[130:131]
	v_pk_fma_f32 v[144:145], v[32:33], v[136:137], v[144:145]
	v_mul_f32_e32 v124, 0xbfb8aa3b, v130
	v_exp_f32_e32 v124, v124
	v_pk_fma_f32 v[144:145], v[8:9], v[154:155], v[144:145]
	v_mov_b64_e32 v[160:161], v[68:69]
	v_add_f32_e32 v124, 1.0, v124
	v_rcp_f32_e32 v152, v124
	v_mul_f32_e32 v124, 0xbfb8aa3b, v131
	v_exp_f32_e32 v124, v124
	s_nop 0
	v_add_f32_e32 v124, 1.0, v124
	v_rcp_f32_e32 v153, v124
	s_nop 0
	v_pk_mul_f32 v[156:157], v[130:131], v[152:153]
	v_lshlrev_b32_e32 v152, 16, v125
	v_and_b32_e32 v153, 0xffff0000, v125
	v_pk_fma_f32 v[124:125], v[26:27], v[150:151], v[30:31]
	s_nop 0
	v_pk_fma_f32 v[124:125], v[34:35], v[142:143], v[124:125]
	s_nop 0
	v_pk_fma_f32 v[124:125], v[10:11], v[134:135], v[124:125]
	s_nop 0
	v_pk_fma_f32 v[124:125], v[14:15], v[152:153], v[124:125]
	s_nop 0
	v_mul_f32_e32 v130, 0xbfb8aa3b, v124
	v_mul_f32_e32 v131, 0xbfb8aa3b, v125
	v_exp_f32_e32 v130, v130
	v_exp_f32_e32 v131, v131
	v_add_f32_e32 v130, 1.0, v130
	v_add_f32_e32 v131, 1.0, v131
	v_rcp_f32_e32 v130, v130
	v_rcp_f32_e32 v131, v131
	s_nop 0
	v_pk_mul_f32 v[150:151], v[124:125], v[130:131]
	v_pk_fma_f32 v[124:125], v[16:17], v[148:149], v[20:21]
	v_lshlrev_b32_e32 v130, 16, v126
	v_pk_fma_f32 v[124:125], v[0:1], v[140:141], v[124:125]
	v_and_b32_e32 v131, 0xffff0000, v126
	v_pk_fma_f32 v[124:125], v[4:5], v[132:133], v[124:125]
	s_nop 0
	v_pk_fma_f32 v[124:125], v[36:37], v[130:131], v[124:125]
	s_nop 0
	v_mul_f32_e32 v126, 0xbfb8aa3b, v124
	v_exp_f32_e32 v126, v126
	s_nop 0
	v_add_f32_e32 v126, 1.0, v126
	v_rcp_f32_e32 v148, v126
	v_mul_f32_e32 v126, 0xbfb8aa3b, v125
	v_exp_f32_e32 v126, v126
	s_nop 0
	v_add_f32_e32 v126, 1.0, v126
	v_rcp_f32_e32 v149, v126
	s_nop 0
	v_pk_mul_f32 v[148:149], v[124:125], v[148:149]
	v_lshlrev_b32_e32 v124, 16, v127
	v_and_b32_e32 v125, 0xffff0000, v127
	v_pk_fma_f32 v[126:127], v[18:19], v[146:147], v[22:23]
	v_cvt_pk_bf16_f32 v148, v148, v149
	v_pk_fma_f32 v[126:127], v[2:3], v[138:139], v[126:127]
	s_nop 0
	v_pk_fma_f32 v[126:127], v[6:7], v[128:129], v[126:127]
	s_nop 0
	v_pk_fma_f32 v[126:127], v[38:39], v[124:125], v[126:127]
	s_nop 0
	v_mul_f32_e32 v146, 0xbfb8aa3b, v126
	v_mul_f32_e32 v147, 0xbfb8aa3b, v127
	v_exp_f32_e32 v146, v146
	v_exp_f32_e32 v147, v147
	v_add_f32_e32 v146, 1.0, v146
	v_add_f32_e32 v147, 1.0, v147
	v_rcp_f32_e32 v146, v146
	v_rcp_f32_e32 v147, v147
	s_nop 0
	v_pk_mul_f32 v[126:127], v[126:127], v[146:147]
	s_nop 0
	v_cvt_pk_bf16_f32 v149, v126, v127
	v_or_b32_e32 v126, 13, v200
	v_ashrrev_i32_e32 v127, 31, v126
	v_lshlrev_b64 v[126:127], 12, v[126:127]
	v_cvt_pk_bf16_f32 v146, v156, v157
	v_cvt_pk_bf16_f32 v147, v150, v151
	v_lshl_add_u64 v[126:127], v[198:199], 0, v[126:127]
	global_store_dwordx4 v[126:127], v[146:149], off
	v_lshlrev_b32_e32 v126, 16, v120
	v_and_b32_e32 v127, 0xffff0000, v120
	v_pk_fma_f32 v[144:145], v[12:13], v[126:127], v[144:145]
	v_lshlrev_b32_e32 v148, 16, v122
	v_mul_f32_e32 v120, 0xbfb8aa3b, v144
	v_exp_f32_e32 v120, v120
	v_and_b32_e32 v149, 0xffff0000, v122
	v_lshlrev_b32_e32 v150, 16, v123
	v_and_b32_e32 v151, 0xffff0000, v123
	v_add_f32_e32 v120, 1.0, v120
	v_rcp_f32_e32 v146, v120
	v_mul_f32_e32 v120, 0xbfb8aa3b, v145
	v_exp_f32_e32 v120, v120
	s_waitcnt vmcnt(24)
	v_mov_b64_e32 v[158:159], v[78:79]
	v_mov_b64_e32 v[156:157], v[76:77]
	v_add_f32_e32 v120, 1.0, v120
	v_rcp_f32_e32 v147, v120
	s_nop 0
	v_pk_mul_f32 v[144:145], v[144:145], v[146:147]
	v_lshlrev_b32_e32 v146, 16, v121
	v_and_b32_e32 v147, 0xffff0000, v121
	v_pk_fma_f32 v[120:121], v[26:27], v[142:143], v[30:31]
	s_nop 0
	v_pk_fma_f32 v[120:121], v[34:35], v[134:135], v[120:121]
	s_nop 0
	v_pk_fma_f32 v[120:121], v[10:11], v[152:153], v[120:121]
	s_nop 0
	v_pk_fma_f32 v[120:121], v[14:15], v[146:147], v[120:121]
	s_nop 0
	v_mul_f32_e32 v142, 0xbfb8aa3b, v120
	v_mul_f32_e32 v143, 0xbfb8aa3b, v121
	v_exp_f32_e32 v142, v142
	v_exp_f32_e32 v143, v143
	v_add_f32_e32 v142, 1.0, v142
	v_add_f32_e32 v143, 1.0, v143
	v_rcp_f32_e32 v142, v142
	v_rcp_f32_e32 v143, v143
	s_nop 0
	v_pk_mul_f32 v[142:143], v[120:121], v[142:143]
	v_pk_fma_f32 v[120:121], v[16:17], v[140:141], v[20:21]
	s_nop 0
	v_pk_fma_f32 v[120:121], v[0:1], v[132:133], v[120:121]
	s_nop 0
	v_pk_fma_f32 v[120:121], v[4:5], v[130:131], v[120:121]
	s_nop 0
	v_pk_fma_f32 v[120:121], v[36:37], v[148:149], v[120:121]
	s_nop 0
	v_mul_f32_e32 v122, 0xbfb8aa3b, v120
	v_exp_f32_e32 v122, v122
	s_nop 0
	v_add_f32_e32 v122, 1.0, v122
	v_rcp_f32_e32 v140, v122
	v_mul_f32_e32 v122, 0xbfb8aa3b, v121
	v_exp_f32_e32 v122, v122
	s_nop 0
	v_add_f32_e32 v122, 1.0, v122
	v_rcp_f32_e32 v141, v122
	s_nop 0
	v_pk_mul_f32 v[140:141], v[120:121], v[140:141]
	v_pk_fma_f32 v[120:121], v[18:19], v[138:139], v[22:23]
	s_nop 0
	v_pk_fma_f32 v[120:121], v[2:3], v[128:129], v[120:121]
	s_nop 0
	v_pk_fma_f32 v[120:121], v[6:7], v[124:125], v[120:121]
	s_nop 0
	v_pk_fma_f32 v[120:121], v[38:39], v[150:151], v[120:121]
	s_nop 0
	v_mul_f32_e32 v122, 0xbfb8aa3b, v120
	v_mul_f32_e32 v123, 0xbfb8aa3b, v121
	v_exp_f32_e32 v122, v122
	v_exp_f32_e32 v123, v123
	v_add_f32_e32 v122, 1.0, v122
	v_add_f32_e32 v123, 1.0, v123
	v_rcp_f32_e32 v122, v122
	v_rcp_f32_e32 v123, v123
	s_nop 0
	v_pk_mul_f32 v[138:139], v[120:121], v[122:123]
	s_nop 0
	v_cvt_pk_bf16_f32 v123, v138, v139
	v_or_b32_e32 v138, 14, v200
	v_ashrrev_i32_e32 v139, 31, v138
	v_lshlrev_b64 v[138:139], 12, v[138:139]
	v_cvt_pk_bf16_f32 v120, v144, v145
	v_cvt_pk_bf16_f32 v121, v142, v143
	v_cvt_pk_bf16_f32 v122, v140, v141
	v_lshl_add_u64 v[138:139], v[198:199], 0, v[138:139]
	global_store_dwordx4 v[138:139], v[120:123], off
	s_waitcnt vmcnt(21)
; DI float silu_(float x) { return x * __builtin_amdgcn_rcpf(1.f + __expf(-x)); }
; DI u32x4 pack8f(const float (&f)[8]) { u32x4 r; r[0] = pk2(f[0], f[1]); r[1] = pk2(f[2], f[3]); r[2] = pk2(f[4], f[5]); r[3] = pk2(f[6], f[7]); return r; }
; DI void conv0_phase(const bf16_t* X, const float* w, const float* bias, bf16_t* Y) {
;     ...
;         for (int r = 0; r < 19; ++r) cu[r] = nx[r];
;     ...
;         for (int r = 0; r < 16; ++r) {
;             float cur[8], y[8];
;             unpack8(cu[3 + r], cur);
; #pragma unroll
;             for (int e = 0; e < 8; ++e) { const float v = bb[e] + w0[e] * p3[e] + w1[e] * p2[e] + w2[e] * p1[e] + w3[e] * cur[e]; y[e] = silu_(v); p3[e] = p2[e]; p2[e] = p1[e]; p1[e] = cur[e]; }
;             *(u32x4*)(Y + (size_t)(t0 + r) * 2048 + c0) = pack8f(y);
;         }
;     }
	v_mov_b64_e32 v[142:143], v[94:95]
	v_mov_b64_e32 v[140:141], v[92:93]
	v_pk_fma_f32 v[122:123], v[24:25], v[136:137], v[28:29]
	v_lshlrev_b32_e32 v120, 16, v72
	v_pk_fma_f32 v[122:123], v[32:33], v[154:155], v[122:123]
	v_and_b32_e32 v121, 0xffff0000, v72
	v_pk_fma_f32 v[122:123], v[8:9], v[126:127], v[122:123]
	v_pk_fma_f32 v[126:127], v[16:17], v[132:133], v[20:21]
	v_pk_fma_f32 v[120:121], v[12:13], v[120:121], v[122:123]
	v_pk_fma_f32 v[126:127], v[0:1], v[130:131], v[126:127]
	v_mul_f32_e32 v72, 0xbfb8aa3b, v120
	v_exp_f32_e32 v72, v72
	v_pk_fma_f32 v[126:127], v[4:5], v[148:149], v[126:127]
	s_waitcnt vmcnt(20)
	v_mov_b64_e32 v[138:139], v[98:99]
	v_mov_b64_e32 v[136:137], v[96:97]
	v_add_f32_e32 v72, 1.0, v72
	v_rcp_f32_e32 v122, v72
	v_mul_f32_e32 v72, 0xbfb8aa3b, v121
	v_exp_f32_e32 v72, v72
	v_mov_b32_e32 v200, v194
	v_add_f32_e32 v72, 1.0, v72
	v_rcp_f32_e32 v123, v72
	v_lshlrev_b32_e32 v72, 16, v73
	v_and_b32_e32 v73, 0xffff0000, v73
	v_pk_mul_f32 v[120:121], v[120:121], v[122:123]
	v_pk_fma_f32 v[122:123], v[26:27], v[134:135], v[30:31]
	s_waitcnt vmcnt(19)
	v_mov_b64_e32 v[134:135], v[102:103]
	v_pk_fma_f32 v[122:123], v[34:35], v[152:153], v[122:123]
	v_mov_b64_e32 v[154:155], v[82:83]
	v_pk_fma_f32 v[122:123], v[10:11], v[146:147], v[122:123]
	v_mov_b64_e32 v[146:147], v[90:91]
	v_pk_fma_f32 v[72:73], v[14:15], v[72:73], v[122:123]
	v_mov_b64_e32 v[152:153], v[80:81]
	v_mul_f32_e32 v122, 0xbfb8aa3b, v72
	v_mul_f32_e32 v123, 0xbfb8aa3b, v73
	v_exp_f32_e32 v122, v122
	v_exp_f32_e32 v123, v123
	v_mov_b64_e32 v[144:145], v[88:89]
	v_mov_b64_e32 v[132:133], v[100:101]
	v_add_f32_e32 v122, 1.0, v122
	v_add_f32_e32 v123, 1.0, v123
	v_rcp_f32_e32 v122, v122
	v_rcp_f32_e32 v123, v123
	s_nop 0
	v_pk_mul_f32 v[122:123], v[72:73], v[122:123]
	v_lshlrev_b32_e32 v72, 16, v74
	v_and_b32_e32 v73, 0xffff0000, v74
	v_pk_fma_f32 v[72:73], v[36:37], v[72:73], v[126:127]
	s_nop 0
	v_mul_f32_e32 v74, 0xbfb8aa3b, v72
	v_exp_f32_e32 v74, v74
	s_nop 0
	v_add_f32_e32 v74, 1.0, v74
	v_rcp_f32_e32 v126, v74
	v_mul_f32_e32 v74, 0xbfb8aa3b, v73
	v_exp_f32_e32 v74, v74
	s_nop 0
	v_add_f32_e32 v74, 1.0, v74
	v_rcp_f32_e32 v127, v74
	s_nop 0
	v_pk_mul_f32 v[126:127], v[72:73], v[126:127]
	v_lshlrev_b32_e32 v72, 16, v75
	v_and_b32_e32 v73, 0xffff0000, v75
	v_pk_fma_f32 v[74:75], v[18:19], v[128:129], v[22:23]
	s_waitcnt vmcnt(18)
	v_mov_b64_e32 v[130:131], v[106:107]
	v_pk_fma_f32 v[74:75], v[2:3], v[124:125], v[74:75]
	v_mov_b64_e32 v[128:129], v[104:105]
	v_pk_fma_f32 v[74:75], v[6:7], v[150:151], v[74:75]
	v_mov_b64_e32 v[150:151], v[86:87]
	v_pk_fma_f32 v[72:73], v[38:39], v[72:73], v[74:75]
	v_mov_b64_e32 v[148:149], v[84:85]
	v_mul_f32_e32 v74, 0xbfb8aa3b, v72
	v_mul_f32_e32 v75, 0xbfb8aa3b, v73
	v_exp_f32_e32 v74, v74
	v_exp_f32_e32 v75, v75
	v_add_f32_e32 v74, 1.0, v74
	v_add_f32_e32 v75, 1.0, v75
	v_rcp_f32_e32 v74, v74
	v_rcp_f32_e32 v75, v75
	s_nop 0
	v_pk_mul_f32 v[124:125], v[72:73], v[74:75]
	v_cvt_pk_bf16_f32 v72, v120, v121
	v_or_b32_e32 v120, 15, v215
	v_ashrrev_i32_e32 v121, 31, v120
	v_lshlrev_b64 v[120:121], 12, v[120:121]
	v_cvt_pk_bf16_f32 v73, v122, v123
	v_cvt_pk_bf16_f32 v74, v126, v127
	v_cvt_pk_bf16_f32 v75, v124, v125
	v_lshl_add_u64 v[120:121], v[198:199], 0, v[120:121]
	global_store_dwordx4 v[120:121], v[72:75], off
	s_waitcnt vmcnt(18)
	v_mov_b64_e32 v[126:127], v[110:111]
	s_waitcnt vmcnt(17)
	v_mov_b64_e32 v[122:123], v[114:115]
	s_waitcnt vmcnt(16)
	v_mov_b64_e32 v[72:73], v[116:117]
	v_mov_b64_e32 v[124:125], v[108:109]
	v_mov_b64_e32 v[120:121], v[112:113]
	v_mov_b64_e32 v[74:75], v[118:119]
	s_andn2_b64 exec, exec, s[30:31]
	s_cbranch_execz .LBB0_252
